# v29 + GEMM K-loops: 36 LDS-DMA loads use the scalar-base form (saddr + 32-bit lane offset) instead of a per-load 64-bit VALU address add
# baseline (speedup 1.0000x reference)
.LBB0_247:
	s_add_u32 s4, s44, 0xfffc0080
	s_addc_u32 s5, s45, -1
	s_add_i32 s62, 0, 0x10000
	s_cmp_eq_u32 s61, 12
	s_cselect_b32 s5, s39, s5
	s_cselect_b32 s4, s38, s4
	v_add_u32_e32 v138, s62, v141
	s_cselect_b32 s47, s43, s9
	s_cselect_b32 s46, s42, s8
	s_add_i32 s64, 0, 0x14000
	ds_read_b128 v[144:147], v138
	ds_read_b128 v[148:151], v138 offset:1024
	ds_read_b128 v[152:155], v138 offset:2048
	ds_read_b128 v[156:159], v138 offset:3072
	v_add_u32_e32 v138, s64, v141
	ds_read_b128 v[160:163], v138
	ds_read_b128 v[164:167], v138 offset:1024
	ds_read_b128 v[168:171], v138 offset:2048
	ds_read_b128 v[182:185], v138 offset:3072
	s_add_i32 m0, s13, 0xc000
	ds_read_b128 v[186:189], v143
	ds_read_b128 v[190:193], v143 offset:1024
	ds_read_b128 v[194:197], v143 offset:2048
	ds_read_b128 v[198:201], v143 offset:3072
	ds_read_b128 v[214:217], v143 offset:4096
	ds_read_b128 v[218:221], v143 offset:5120
	ds_read_b128 v[222:225], v143 offset:6144
	ds_read_b128 v[226:229], v143 offset:7168
	global_load_lds_dwordx4 v134, s[44:45]
	s_add_i32 m0, s13, 0xe000
	s_nop 0
	global_load_lds_dwordx4 v136, s[44:45]
	s_waitcnt vmcnt(8)
	s_waitcnt lgkmcnt(0)
	s_barrier
	s_waitcnt lgkmcnt(0)
	v_mfma_f32_16x16x32_bf16 v[124:127], v[144:147], v[186:189], v[124:127]
	v_mfma_f32_16x16x32_bf16 v[120:123], v[152:155], v[186:189], v[120:123]
	v_mfma_f32_16x16x32_bf16 v[112:115], v[144:147], v[194:197], v[112:115]
	v_mfma_f32_16x16x32_bf16 v[104:107], v[152:155], v[194:197], v[104:107]
	v_mfma_f32_16x16x32_bf16 v[96:99], v[144:147], v[214:217], v[96:99]
	v_mfma_f32_16x16x32_bf16 v[88:91], v[152:155], v[214:217], v[88:91]
	v_mfma_f32_16x16x32_bf16 v[80:83], v[144:147], v[222:225], v[80:83]
	v_mfma_f32_16x16x32_bf16 v[72:75], v[152:155], v[222:225], v[72:75]
	v_mfma_f32_16x16x32_bf16 v[124:127], v[148:151], v[190:193], v[124:127]
	v_mfma_f32_16x16x32_bf16 v[120:123], v[156:159], v[190:193], v[120:123]
	v_mfma_f32_16x16x32_bf16 v[112:115], v[148:151], v[198:201], v[112:115]
	v_mfma_f32_16x16x32_bf16 v[104:107], v[156:159], v[198:201], v[104:107]
	v_mfma_f32_16x16x32_bf16 v[96:99], v[148:151], v[218:221], v[96:99]
	v_mfma_f32_16x16x32_bf16 v[88:91], v[156:159], v[218:221], v[88:91]
	v_mfma_f32_16x16x32_bf16 v[80:83], v[148:151], v[226:229], v[80:83]
	v_mfma_f32_16x16x32_bf16 v[72:75], v[156:159], v[226:229], v[72:75]
	v_mfma_f32_16x16x32_bf16 v[116:119], v[160:163], v[186:189], v[116:119]
	v_mfma_f32_16x16x32_bf16 v[108:111], v[168:171], v[186:189], v[108:111]
	v_mfma_f32_16x16x32_bf16 v[100:103], v[160:163], v[194:197], v[100:103]
	v_mfma_f32_16x16x32_bf16 v[92:95], v[168:171], v[194:197], v[92:95]
	v_mfma_f32_16x16x32_bf16 v[84:87], v[160:163], v[214:217], v[84:87]
	v_mfma_f32_16x16x32_bf16 v[76:79], v[168:171], v[214:217], v[76:79]
	v_mfma_f32_16x16x32_bf16 v[68:71], v[160:163], v[222:225], v[68:71]
	v_mfma_f32_16x16x32_bf16 v[64:67], v[168:171], v[222:225], v[64:67]
	v_mfma_f32_16x16x32_bf16 v[116:119], v[164:167], v[190:193], v[116:119]
	v_mfma_f32_16x16x32_bf16 v[108:111], v[182:185], v[190:193], v[108:111]
	v_mfma_f32_16x16x32_bf16 v[100:103], v[164:167], v[198:201], v[100:103]
	v_mfma_f32_16x16x32_bf16 v[92:95], v[182:185], v[198:201], v[92:95]
	v_mfma_f32_16x16x32_bf16 v[84:87], v[164:167], v[218:221], v[84:87]
	v_mfma_f32_16x16x32_bf16 v[76:79], v[182:185], v[218:221], v[76:79]
	v_mfma_f32_16x16x32_bf16 v[68:71], v[164:167], v[226:229], v[68:71]
	v_mfma_f32_16x16x32_bf16 v[64:67], v[182:185], v[226:229], v[64:67]
	s_barrier
	s_add_i32 s62, s62, s11
	v_lshl_add_u64 v[138:139], s[46:47], 0, v[172:173]
	s_mov_b32 m0, s62
	ds_read_b128 v[186:189], v143 offset:16384
	ds_read_b128 v[190:193], v143 offset:17408
	ds_read_b128 v[194:197], v143 offset:18432
	ds_read_b128 v[198:201], v143 offset:19456
	ds_read_b128 v[214:217], v143 offset:20480
	ds_read_b128 v[218:221], v143 offset:21504
	ds_read_b128 v[222:225], v143 offset:22528
	ds_read_b128 v[226:229], v143 offset:23552
	global_load_lds_dwordx4 v[138:139], off
	s_add_i32 m0, s62, 0x2000
	s_add_u32 s62, s46, 0x40000
	v_lshl_add_u64 v[202:203], s[46:47], 0, v[128:129]
	s_addc_u32 s63, s47, 0
	s_add_i32 s64, s64, s11
	global_load_lds_dwordx4 v[202:203], off
	s_mov_b32 m0, s64
	v_lshl_add_u64 v[232:233], s[4:5], 0, v[130:131]
	global_load_lds_dwordx4 v172, s[62:63]
	s_add_i32 m0, s64, 0x2000
	s_nop 0
	global_load_lds_dwordx4 v128, s[62:63]
	v_lshl_add_u64 v[230:231], s[4:5], 0, v[132:133]
	s_mov_b32 m0, s13
	s_nop 0
	global_load_lds_dwordx4 v[230:231], off
	s_mov_b32 m0, s26
	s_nop 0
	global_load_lds_dwordx4 v[232:233], off
	s_waitcnt vmcnt(8)
	s_waitcnt lgkmcnt(0)
	s_barrier
	s_waitcnt lgkmcnt(0)
	v_mfma_f32_16x16x32_bf16 v[60:63], v[144:147], v[186:189], v[60:63]
	v_mfma_f32_16x16x32_bf16 v[56:59], v[152:155], v[186:189], v[56:59]
	v_mfma_f32_16x16x32_bf16 v[48:51], v[144:147], v[194:197], v[48:51]
	v_mfma_f32_16x16x32_bf16 v[40:43], v[152:155], v[194:197], v[40:43]
	v_mfma_f32_16x16x32_bf16 v[32:35], v[144:147], v[214:217], v[32:35]
	v_mfma_f32_16x16x32_bf16 v[24:27], v[152:155], v[214:217], v[24:27]
	v_mfma_f32_16x16x32_bf16 v[16:19], v[144:147], v[222:225], v[16:19]
	v_mfma_f32_16x16x32_bf16 v[8:11], v[152:155], v[222:225], v[8:11]
	v_mfma_f32_16x16x32_bf16 v[60:63], v[148:151], v[190:193], v[60:63]
	v_mfma_f32_16x16x32_bf16 v[56:59], v[156:159], v[190:193], v[56:59]
	v_mfma_f32_16x16x32_bf16 v[48:51], v[148:151], v[198:201], v[48:51]
	v_mfma_f32_16x16x32_bf16 v[40:43], v[156:159], v[198:201], v[40:43]
	v_mfma_f32_16x16x32_bf16 v[32:35], v[148:151], v[218:221], v[32:35]
	v_mfma_f32_16x16x32_bf16 v[24:27], v[156:159], v[218:221], v[24:27]
	v_mfma_f32_16x16x32_bf16 v[16:19], v[148:151], v[226:229], v[16:19]
	v_mfma_f32_16x16x32_bf16 v[8:11], v[156:159], v[226:229], v[8:11]
	v_mfma_f32_16x16x32_bf16 v[52:55], v[160:163], v[186:189], v[52:55]
	v_mfma_f32_16x16x32_bf16 v[44:47], v[168:171], v[186:189], v[44:47]
	v_mfma_f32_16x16x32_bf16 v[36:39], v[160:163], v[194:197], v[36:39]
	v_mfma_f32_16x16x32_bf16 v[28:31], v[168:171], v[194:197], v[28:31]
	v_mfma_f32_16x16x32_bf16 v[20:23], v[160:163], v[214:217], v[20:23]
	v_mfma_f32_16x16x32_bf16 v[12:15], v[168:171], v[214:217], v[12:15]
	v_mfma_f32_16x16x32_bf16 v[4:7], v[160:163], v[222:225], v[4:7]
	v_mfma_f32_16x16x32_bf16 v[0:3], v[168:171], v[222:225], v[0:3]
	v_mfma_f32_16x16x32_bf16 v[52:55], v[164:167], v[190:193], v[52:55]
	v_mfma_f32_16x16x32_bf16 v[44:47], v[182:185], v[190:193], v[44:47]
	v_mfma_f32_16x16x32_bf16 v[36:39], v[164:167], v[198:201], v[36:39]
	v_mfma_f32_16x16x32_bf16 v[28:31], v[182:185], v[198:201], v[28:31]
	v_mfma_f32_16x16x32_bf16 v[20:23], v[164:167], v[218:221], v[20:23]
	v_mfma_f32_16x16x32_bf16 v[12:15], v[182:185], v[218:221], v[12:15]
	v_mfma_f32_16x16x32_bf16 v[4:7], v[164:167], v[226:229], v[4:7]
	v_mfma_f32_16x16x32_bf16 v[0:3], v[182:185], v[226:229], v[0:3]
	s_barrier
	s_add_i32 s62, 0, 0x18000
	s_add_i32 s63, 0, 0x1c000
	v_add_u32_e32 v156, s62, v141
	v_add_u32_e32 v182, s63, v141
	ds_read_b128 v[144:147], v156
	ds_read_b128 v[148:151], v156 offset:1024
	ds_read_b128 v[152:155], v156 offset:2048
	ds_read_b128 v[156:159], v156 offset:3072
	ds_read_b128 v[160:163], v182
	ds_read_b128 v[164:167], v182 offset:1024
	ds_read_b128 v[168:171], v182 offset:2048
	ds_read_b128 v[182:185], v182 offset:3072
	s_add_u32 s4, s4, 0x40000
	s_addc_u32 s5, s5, 0
	s_mov_b32 m0, s31
	ds_read_b128 v[186:189], v143 offset:32768
	ds_read_b128 v[190:193], v143 offset:33792
	ds_read_b128 v[194:197], v143 offset:34816
	ds_read_b128 v[198:201], v143 offset:35840
	ds_read_b128 v[214:217], v143 offset:36864
	ds_read_b128 v[218:221], v143 offset:37888
	ds_read_b128 v[222:225], v143 offset:38912
	ds_read_b128 v[226:229], v143 offset:39936
	global_load_lds_dwordx4 v132, s[4:5]
	s_mov_b32 m0, s35
	s_nop 0
	global_load_lds_dwordx4 v130, s[4:5]
	s_waitcnt vmcnt(8)
	s_waitcnt lgkmcnt(0)
	s_barrier
	s_waitcnt lgkmcnt(0)
	v_mfma_f32_16x16x32_bf16 v[124:127], v[144:147], v[186:189], v[124:127]
	v_mfma_f32_16x16x32_bf16 v[120:123], v[152:155], v[186:189], v[120:123]
	v_mfma_f32_16x16x32_bf16 v[112:115], v[144:147], v[194:197], v[112:115]
	v_mfma_f32_16x16x32_bf16 v[104:107], v[152:155], v[194:197], v[104:107]
	v_mfma_f32_16x16x32_bf16 v[96:99], v[144:147], v[214:217], v[96:99]
	v_mfma_f32_16x16x32_bf16 v[88:91], v[152:155], v[214:217], v[88:91]
	v_mfma_f32_16x16x32_bf16 v[80:83], v[144:147], v[222:225], v[80:83]
	v_mfma_f32_16x16x32_bf16 v[72:75], v[152:155], v[222:225], v[72:75]
	v_mfma_f32_16x16x32_bf16 v[124:127], v[148:151], v[190:193], v[124:127]
	v_mfma_f32_16x16x32_bf16 v[120:123], v[156:159], v[190:193], v[120:123]
	v_mfma_f32_16x16x32_bf16 v[112:115], v[148:151], v[198:201], v[112:115]
	v_mfma_f32_16x16x32_bf16 v[104:107], v[156:159], v[198:201], v[104:107]
	v_mfma_f32_16x16x32_bf16 v[96:99], v[148:151], v[218:221], v[96:99]
	v_mfma_f32_16x16x32_bf16 v[88:91], v[156:159], v[218:221], v[88:91]
	v_mfma_f32_16x16x32_bf16 v[80:83], v[148:151], v[226:229], v[80:83]
	v_mfma_f32_16x16x32_bf16 v[72:75], v[156:159], v[226:229], v[72:75]
	v_mfma_f32_16x16x32_bf16 v[116:119], v[160:163], v[186:189], v[116:119]
	v_mfma_f32_16x16x32_bf16 v[108:111], v[168:171], v[186:189], v[108:111]
	v_mfma_f32_16x16x32_bf16 v[100:103], v[160:163], v[194:197], v[100:103]
	v_mfma_f32_16x16x32_bf16 v[92:95], v[168:171], v[194:197], v[92:95]
	v_mfma_f32_16x16x32_bf16 v[84:87], v[160:163], v[214:217], v[84:87]
	v_mfma_f32_16x16x32_bf16 v[76:79], v[168:171], v[214:217], v[76:79]
	v_mfma_f32_16x16x32_bf16 v[68:71], v[160:163], v[222:225], v[68:71]
	v_mfma_f32_16x16x32_bf16 v[64:67], v[168:171], v[222:225], v[64:67]
	v_mfma_f32_16x16x32_bf16 v[116:119], v[164:167], v[190:193], v[116:119]
	v_mfma_f32_16x16x32_bf16 v[108:111], v[182:185], v[190:193], v[108:111]
	v_mfma_f32_16x16x32_bf16 v[100:103], v[164:167], v[198:201], v[100:103]
	v_mfma_f32_16x16x32_bf16 v[92:95], v[182:185], v[198:201], v[92:95]
	v_mfma_f32_16x16x32_bf16 v[84:87], v[164:167], v[218:221], v[84:87]
	v_mfma_f32_16x16x32_bf16 v[76:79], v[182:185], v[218:221], v[76:79]
	v_mfma_f32_16x16x32_bf16 v[68:71], v[164:167], v[226:229], v[68:71]
	v_mfma_f32_16x16x32_bf16 v[64:67], v[182:185], v[226:229], v[64:67]
	s_barrier
	s_add_i32 s4, s62, s11
	v_lshl_add_u64 v[138:139], v[138:139], 0, s[36:37]
	s_mov_b32 m0, s4
	ds_read_b128 v[186:189], v143 offset:49152
	ds_read_b128 v[190:193], v143 offset:50176
	ds_read_b128 v[194:197], v143 offset:51200
	ds_read_b128 v[198:201], v143 offset:52224
	ds_read_b128 v[214:217], v143 offset:53248
	ds_read_b128 v[218:221], v143 offset:54272
	ds_read_b128 v[222:225], v143 offset:55296
	ds_read_b128 v[226:229], v143 offset:56320
	global_load_lds_dwordx4 v[138:139], off
	s_add_i32 m0, s4, 0x2000
	s_add_u32 s4, s46, 0x40080
	v_lshl_add_u64 v[138:139], v[202:203], 0, s[36:37]
	s_addc_u32 s5, s47, 0
	s_add_i32 s46, s63, s11
	global_load_lds_dwordx4 v[138:139], off
	s_mov_b32 m0, s46
	s_nop 0
	global_load_lds_dwordx4 v172, s[4:5]
	s_add_i32 m0, s46, 0x2000
	s_nop 0
	global_load_lds_dwordx4 v128, s[4:5]
	v_lshl_add_u64 v[138:139], v[230:231], 0, s[36:37]
	s_mov_b32 m0, s48
	s_nop 0
	global_load_lds_dwordx4 v[138:139], off
	v_lshl_add_u64 v[138:139], v[232:233], 0, s[36:37]
	s_mov_b32 m0, s49
	s_nop 0
	global_load_lds_dwordx4 v[138:139], off
	s_waitcnt vmcnt(8)
	s_waitcnt lgkmcnt(0)
	s_barrier
	s_waitcnt lgkmcnt(0)
	v_mfma_f32_16x16x32_bf16 v[60:63], v[144:147], v[186:189], v[60:63]
	v_mfma_f32_16x16x32_bf16 v[56:59], v[152:155], v[186:189], v[56:59]
	v_mfma_f32_16x16x32_bf16 v[48:51], v[144:147], v[194:197], v[48:51]
	v_mfma_f32_16x16x32_bf16 v[40:43], v[152:155], v[194:197], v[40:43]
	v_mfma_f32_16x16x32_bf16 v[32:35], v[144:147], v[214:217], v[32:35]
	v_mfma_f32_16x16x32_bf16 v[24:27], v[152:155], v[214:217], v[24:27]
	v_mfma_f32_16x16x32_bf16 v[16:19], v[144:147], v[222:225], v[16:19]
	v_mfma_f32_16x16x32_bf16 v[8:11], v[152:155], v[222:225], v[8:11]
	v_mfma_f32_16x16x32_bf16 v[60:63], v[148:151], v[190:193], v[60:63]
	v_mfma_f32_16x16x32_bf16 v[56:59], v[156:159], v[190:193], v[56:59]
	v_mfma_f32_16x16x32_bf16 v[48:51], v[148:151], v[198:201], v[48:51]
	v_mfma_f32_16x16x32_bf16 v[40:43], v[156:159], v[198:201], v[40:43]
	v_mfma_f32_16x16x32_bf16 v[32:35], v[148:151], v[218:221], v[32:35]
	v_mfma_f32_16x16x32_bf16 v[24:27], v[156:159], v[218:221], v[24:27]
	v_mfma_f32_16x16x32_bf16 v[16:19], v[148:151], v[226:229], v[16:19]
	v_mfma_f32_16x16x32_bf16 v[8:11], v[156:159], v[226:229], v[8:11]
	v_mfma_f32_16x16x32_bf16 v[52:55], v[160:163], v[186:189], v[52:55]
	v_mfma_f32_16x16x32_bf16 v[44:47], v[168:171], v[186:189], v[44:47]
	v_mfma_f32_16x16x32_bf16 v[36:39], v[160:163], v[194:197], v[36:39]
	v_mfma_f32_16x16x32_bf16 v[28:31], v[168:171], v[194:197], v[28:31]
	v_mfma_f32_16x16x32_bf16 v[20:23], v[160:163], v[214:217], v[20:23]
	v_mfma_f32_16x16x32_bf16 v[12:15], v[168:171], v[214:217], v[12:15]
	v_mfma_f32_16x16x32_bf16 v[4:7], v[160:163], v[222:225], v[4:7]
	v_mfma_f32_16x16x32_bf16 v[0:3], v[168:171], v[222:225], v[0:3]
	v_mfma_f32_16x16x32_bf16 v[52:55], v[164:167], v[190:193], v[52:55]
	v_mfma_f32_16x16x32_bf16 v[44:47], v[182:185], v[190:193], v[44:47]
	v_mfma_f32_16x16x32_bf16 v[36:39], v[164:167], v[198:201], v[36:39]
	v_mfma_f32_16x16x32_bf16 v[28:31], v[182:185], v[198:201], v[28:31]
	v_mfma_f32_16x16x32_bf16 v[20:23], v[164:167], v[218:221], v[20:23]
	v_mfma_f32_16x16x32_bf16 v[12:15], v[182:185], v[218:221], v[12:15]
	v_mfma_f32_16x16x32_bf16 v[4:7], v[164:167], v[226:229], v[4:7]
	v_mfma_f32_16x16x32_bf16 v[0:3], v[182:185], v[226:229], v[0:3]
	s_barrier
	s_add_i32 s61, s61, 2
	s_add_u32 s44, s44, 0x100
	s_addc_u32 s45, s45, 0
	s_add_u32 s8, s8, 0x100
	s_addc_u32 s9, s9, 0
	s_cmp_gt_u32 s61, 13
	s_cbranch_scc0 .LBB0_247
	s_and_b64 vcc, exec, s[28:29]
	s_cbranch_vccz .LBB0_250
	s_barrier

.LBB0_914:
	s_add_u32 s4, s56, 0xfffc0080
	s_addc_u32 s5, s57, -1
	s_add_i32 s71, 0, 0x10000
	s_cmp_eq_u32 s70, 12
	s_cselect_b32 s5, s45, s5
	s_cselect_b32 s4, s68, s4
	s_cselect_b32 s59, s39, s9
	s_cselect_b32 s58, s69, s8
	s_add_i32 s74, 0, 0x14000
	v_add_u32_e32 v132, s71, v215
	v_add_u32_e32 v156, s74, v215
	ds_read_b128 v[120:123], v132
	ds_read_b128 v[124:127], v132 offset:1024
	ds_read_b128 v[128:131], v132 offset:2048
	ds_read_b128 v[132:135], v132 offset:3072
	ds_read_b128 v[144:147], v156
	ds_read_b128 v[148:151], v156 offset:1024
	ds_read_b128 v[152:155], v156 offset:2048
	ds_read_b128 v[156:159], v156 offset:3072
	s_add_i32 m0, s51, 0xc000
	ds_read_b128 v[160:163], v217
	ds_read_b128 v[164:167], v217 offset:1024
	ds_read_b128 v[168:171], v217 offset:2048
	ds_read_b128 v[192:195], v217 offset:3072
	ds_read_b128 v[196:199], v217 offset:4096
	ds_read_b128 v[200:203], v217 offset:5120
	ds_read_b128 v[218:221], v217 offset:6144
	ds_read_b128 v[222:225], v217 offset:7168
	global_load_lds_dwordx4 v188, s[56:57]
	s_add_i32 m0, s51, 0xe000
	s_nop 0
	global_load_lds_dwordx4 v190, s[56:57]
	s_waitcnt vmcnt(8)
	s_waitcnt lgkmcnt(0)
	s_barrier
	s_waitcnt lgkmcnt(0)
	v_mfma_f32_16x16x32_bf16 v[140:143], v[120:123], v[160:163], v[140:143]
	v_mfma_f32_16x16x32_bf16 v[136:139], v[128:131], v[160:163], v[136:139]
	v_mfma_f32_16x16x32_bf16 v[108:111], v[120:123], v[168:171], v[108:111]
	v_mfma_f32_16x16x32_bf16 v[104:107], v[128:131], v[168:171], v[104:107]
	v_mfma_f32_16x16x32_bf16 v[96:99], v[120:123], v[196:199], v[96:99]
	v_mfma_f32_16x16x32_bf16 v[88:91], v[128:131], v[196:199], v[88:91]
	v_mfma_f32_16x16x32_bf16 v[80:83], v[120:123], v[218:221], v[80:83]
	v_mfma_f32_16x16x32_bf16 v[72:75], v[128:131], v[218:221], v[72:75]
	v_mfma_f32_16x16x32_bf16 v[140:143], v[124:127], v[164:167], v[140:143]
	v_mfma_f32_16x16x32_bf16 v[136:139], v[132:135], v[164:167], v[136:139]
	v_mfma_f32_16x16x32_bf16 v[108:111], v[124:127], v[192:195], v[108:111]
	v_mfma_f32_16x16x32_bf16 v[104:107], v[132:135], v[192:195], v[104:107]
	v_mfma_f32_16x16x32_bf16 v[96:99], v[124:127], v[200:203], v[96:99]
	v_mfma_f32_16x16x32_bf16 v[88:91], v[132:135], v[200:203], v[88:91]
	v_mfma_f32_16x16x32_bf16 v[80:83], v[124:127], v[222:225], v[80:83]
	v_mfma_f32_16x16x32_bf16 v[72:75], v[132:135], v[222:225], v[72:75]
	v_mfma_f32_16x16x32_bf16 v[116:119], v[144:147], v[160:163], v[116:119]
	v_mfma_f32_16x16x32_bf16 v[112:115], v[152:155], v[160:163], v[112:115]
	v_mfma_f32_16x16x32_bf16 v[100:103], v[144:147], v[168:171], v[100:103]
	v_mfma_f32_16x16x32_bf16 v[92:95], v[152:155], v[168:171], v[92:95]
	v_mfma_f32_16x16x32_bf16 v[84:87], v[144:147], v[196:199], v[84:87]
	v_mfma_f32_16x16x32_bf16 v[76:79], v[152:155], v[196:199], v[76:79]
	v_mfma_f32_16x16x32_bf16 v[68:71], v[144:147], v[218:221], v[68:71]
	v_mfma_f32_16x16x32_bf16 v[64:67], v[152:155], v[218:221], v[64:67]
	v_mfma_f32_16x16x32_bf16 v[116:119], v[148:151], v[164:167], v[116:119]
	v_mfma_f32_16x16x32_bf16 v[112:115], v[156:159], v[164:167], v[112:115]
	v_mfma_f32_16x16x32_bf16 v[100:103], v[148:151], v[192:195], v[100:103]
	v_mfma_f32_16x16x32_bf16 v[92:95], v[156:159], v[192:195], v[92:95]
	v_mfma_f32_16x16x32_bf16 v[84:87], v[148:151], v[200:203], v[84:87]
	v_mfma_f32_16x16x32_bf16 v[76:79], v[156:159], v[200:203], v[76:79]
	v_mfma_f32_16x16x32_bf16 v[68:71], v[148:151], v[222:225], v[68:71]
	v_mfma_f32_16x16x32_bf16 v[64:67], v[156:159], v[222:225], v[64:67]
	s_barrier
	s_add_i32 s71, s71, s31
	v_lshl_add_u64 v[226:227], s[58:59], 0, v[172:173]
	s_mov_b32 m0, s71
	ds_read_b128 v[160:163], v217 offset:16384
	ds_read_b128 v[164:167], v217 offset:17408
	ds_read_b128 v[168:171], v217 offset:18432
	ds_read_b128 v[192:195], v217 offset:19456
	ds_read_b128 v[196:199], v217 offset:20480
	ds_read_b128 v[200:203], v217 offset:21504
	ds_read_b128 v[218:221], v217 offset:22528
	ds_read_b128 v[222:225], v217 offset:23552
	global_load_lds_dwordx4 v[226:227], off
	s_add_i32 m0, s71, 0x2000
	s_add_u32 s72, s58, 0x40000
	v_lshl_add_u64 v[228:229], s[58:59], 0, v[182:183]
	s_addc_u32 s73, s59, 0
	s_add_i32 s71, s74, s31
	global_load_lds_dwordx4 v[228:229], off
	s_mov_b32 m0, s71
	v_lshl_add_u64 v[232:233], s[4:5], 0, v[184:185]
	global_load_lds_dwordx4 v172, s[72:73]
	s_add_i32 m0, s71, 0x2000
	s_nop 0
	global_load_lds_dwordx4 v182, s[72:73]
	v_lshl_add_u64 v[230:231], s[4:5], 0, v[186:187]
	s_mov_b32 m0, s51
	s_nop 0
	global_load_lds_dwordx4 v[230:231], off
	s_mov_b32 m0, s60
	s_nop 0
	global_load_lds_dwordx4 v[232:233], off
	s_waitcnt vmcnt(8)
	s_waitcnt lgkmcnt(0)
	s_barrier
	s_waitcnt lgkmcnt(0)
	v_mfma_f32_16x16x32_bf16 v[60:63], v[120:123], v[160:163], v[60:63]
	v_mfma_f32_16x16x32_bf16 v[56:59], v[128:131], v[160:163], v[56:59]
	v_mfma_f32_16x16x32_bf16 v[48:51], v[120:123], v[168:171], v[48:51]
	v_mfma_f32_16x16x32_bf16 v[40:43], v[128:131], v[168:171], v[40:43]
	v_mfma_f32_16x16x32_bf16 v[32:35], v[120:123], v[196:199], v[32:35]
	v_mfma_f32_16x16x32_bf16 v[24:27], v[128:131], v[196:199], v[24:27]
	v_mfma_f32_16x16x32_bf16 v[16:19], v[120:123], v[218:221], v[16:19]
	v_mfma_f32_16x16x32_bf16 v[8:11], v[128:131], v[218:221], v[8:11]
	v_mfma_f32_16x16x32_bf16 v[60:63], v[124:127], v[164:167], v[60:63]
	v_mfma_f32_16x16x32_bf16 v[56:59], v[132:135], v[164:167], v[56:59]
	v_mfma_f32_16x16x32_bf16 v[48:51], v[124:127], v[192:195], v[48:51]
	v_mfma_f32_16x16x32_bf16 v[40:43], v[132:135], v[192:195], v[40:43]
	v_mfma_f32_16x16x32_bf16 v[32:35], v[124:127], v[200:203], v[32:35]
	v_mfma_f32_16x16x32_bf16 v[24:27], v[132:135], v[200:203], v[24:27]
	v_mfma_f32_16x16x32_bf16 v[16:19], v[124:127], v[222:225], v[16:19]
	v_mfma_f32_16x16x32_bf16 v[8:11], v[132:135], v[222:225], v[8:11]
	v_mfma_f32_16x16x32_bf16 v[52:55], v[144:147], v[160:163], v[52:55]
	v_mfma_f32_16x16x32_bf16 v[44:47], v[152:155], v[160:163], v[44:47]
	v_mfma_f32_16x16x32_bf16 v[36:39], v[144:147], v[168:171], v[36:39]
	v_mfma_f32_16x16x32_bf16 v[28:31], v[152:155], v[168:171], v[28:31]
	v_mfma_f32_16x16x32_bf16 v[20:23], v[144:147], v[196:199], v[20:23]
	v_mfma_f32_16x16x32_bf16 v[12:15], v[152:155], v[196:199], v[12:15]
	v_mfma_f32_16x16x32_bf16 v[4:7], v[144:147], v[218:221], v[4:7]
	v_mfma_f32_16x16x32_bf16 v[0:3], v[152:155], v[218:221], v[0:3]
	v_mfma_f32_16x16x32_bf16 v[52:55], v[148:151], v[164:167], v[52:55]
	v_mfma_f32_16x16x32_bf16 v[44:47], v[156:159], v[164:167], v[44:47]
	v_mfma_f32_16x16x32_bf16 v[36:39], v[148:151], v[192:195], v[36:39]
	v_mfma_f32_16x16x32_bf16 v[28:31], v[156:159], v[192:195], v[28:31]
	v_mfma_f32_16x16x32_bf16 v[20:23], v[148:151], v[200:203], v[20:23]
	v_mfma_f32_16x16x32_bf16 v[12:15], v[156:159], v[200:203], v[12:15]
	v_mfma_f32_16x16x32_bf16 v[4:7], v[148:151], v[222:225], v[4:7]
	v_mfma_f32_16x16x32_bf16 v[0:3], v[156:159], v[222:225], v[0:3]
	s_barrier
	s_add_i32 s71, 0, 0x18000
	s_add_i32 s72, 0, 0x1c000
	v_add_u32_e32 v132, s71, v215
	v_add_u32_e32 v156, s72, v215
	ds_read_b128 v[120:123], v132
	ds_read_b128 v[124:127], v132 offset:1024
	ds_read_b128 v[128:131], v132 offset:2048
	ds_read_b128 v[132:135], v132 offset:3072
	ds_read_b128 v[144:147], v156
	ds_read_b128 v[148:151], v156 offset:1024
	ds_read_b128 v[152:155], v156 offset:2048
	ds_read_b128 v[156:159], v156 offset:3072
	s_add_u32 s4, s4, 0x40000
	s_addc_u32 s5, s5, 0
	s_mov_b32 m0, s61
	ds_read_b128 v[160:163], v217 offset:32768
	ds_read_b128 v[164:167], v217 offset:33792
	ds_read_b128 v[168:171], v217 offset:34816
	ds_read_b128 v[192:195], v217 offset:35840
	ds_read_b128 v[196:199], v217 offset:36864
	ds_read_b128 v[200:203], v217 offset:37888
	ds_read_b128 v[218:221], v217 offset:38912
	ds_read_b128 v[222:225], v217 offset:39936
	global_load_lds_dwordx4 v186, s[4:5]
	s_mov_b32 m0, s62
	s_nop 0
	global_load_lds_dwordx4 v184, s[4:5]
	s_waitcnt vmcnt(8)
	s_waitcnt lgkmcnt(0)
	s_barrier
	s_waitcnt lgkmcnt(0)
	v_mfma_f32_16x16x32_bf16 v[140:143], v[120:123], v[160:163], v[140:143]
	v_mfma_f32_16x16x32_bf16 v[136:139], v[128:131], v[160:163], v[136:139]
	v_mfma_f32_16x16x32_bf16 v[108:111], v[120:123], v[168:171], v[108:111]
	v_mfma_f32_16x16x32_bf16 v[104:107], v[128:131], v[168:171], v[104:107]
	v_mfma_f32_16x16x32_bf16 v[96:99], v[120:123], v[196:199], v[96:99]
	v_mfma_f32_16x16x32_bf16 v[88:91], v[128:131], v[196:199], v[88:91]
	v_mfma_f32_16x16x32_bf16 v[80:83], v[120:123], v[218:221], v[80:83]
	v_mfma_f32_16x16x32_bf16 v[72:75], v[128:131], v[218:221], v[72:75]
	v_mfma_f32_16x16x32_bf16 v[140:143], v[124:127], v[164:167], v[140:143]
	v_mfma_f32_16x16x32_bf16 v[136:139], v[132:135], v[164:167], v[136:139]
	v_mfma_f32_16x16x32_bf16 v[108:111], v[124:127], v[192:195], v[108:111]
	v_mfma_f32_16x16x32_bf16 v[104:107], v[132:135], v[192:195], v[104:107]
	v_mfma_f32_16x16x32_bf16 v[96:99], v[124:127], v[200:203], v[96:99]
	v_mfma_f32_16x16x32_bf16 v[88:91], v[132:135], v[200:203], v[88:91]
	v_mfma_f32_16x16x32_bf16 v[80:83], v[124:127], v[222:225], v[80:83]
	v_mfma_f32_16x16x32_bf16 v[72:75], v[132:135], v[222:225], v[72:75]
	v_mfma_f32_16x16x32_bf16 v[116:119], v[144:147], v[160:163], v[116:119]
	v_mfma_f32_16x16x32_bf16 v[112:115], v[152:155], v[160:163], v[112:115]
	v_mfma_f32_16x16x32_bf16 v[100:103], v[144:147], v[168:171], v[100:103]
	v_mfma_f32_16x16x32_bf16 v[92:95], v[152:155], v[168:171], v[92:95]
	v_mfma_f32_16x16x32_bf16 v[84:87], v[144:147], v[196:199], v[84:87]
	v_mfma_f32_16x16x32_bf16 v[76:79], v[152:155], v[196:199], v[76:79]
	v_mfma_f32_16x16x32_bf16 v[68:71], v[144:147], v[218:221], v[68:71]
	v_mfma_f32_16x16x32_bf16 v[64:67], v[152:155], v[218:221], v[64:67]
	v_mfma_f32_16x16x32_bf16 v[116:119], v[148:151], v[164:167], v[116:119]
	v_mfma_f32_16x16x32_bf16 v[112:115], v[156:159], v[164:167], v[112:115]
	v_mfma_f32_16x16x32_bf16 v[100:103], v[148:151], v[192:195], v[100:103]
	v_mfma_f32_16x16x32_bf16 v[92:95], v[156:159], v[192:195], v[92:95]
	v_mfma_f32_16x16x32_bf16 v[84:87], v[148:151], v[200:203], v[84:87]
	v_mfma_f32_16x16x32_bf16 v[76:79], v[156:159], v[200:203], v[76:79]
	v_mfma_f32_16x16x32_bf16 v[68:71], v[148:151], v[222:225], v[68:71]
	v_mfma_f32_16x16x32_bf16 v[64:67], v[156:159], v[222:225], v[64:67]
	s_barrier
	s_add_i32 s4, s71, s31
	v_lshl_add_u64 v[226:227], v[226:227], 0, s[36:37]
	s_mov_b32 m0, s4
	ds_read_b128 v[160:163], v217 offset:49152
	ds_read_b128 v[164:167], v217 offset:50176
	ds_read_b128 v[168:171], v217 offset:51200
	ds_read_b128 v[192:195], v217 offset:52224
	ds_read_b128 v[196:199], v217 offset:53248
	ds_read_b128 v[200:203], v217 offset:54272
	ds_read_b128 v[218:221], v217 offset:55296
	ds_read_b128 v[222:225], v217 offset:56320
	global_load_lds_dwordx4 v[226:227], off
	s_add_i32 m0, s4, 0x2000
	s_add_u32 s4, s58, 0x40080
	v_lshl_add_u64 v[226:227], v[228:229], 0, s[36:37]
	s_addc_u32 s5, s59, 0
	s_add_i32 s58, s72, s31
	global_load_lds_dwordx4 v[226:227], off
	s_mov_b32 m0, s58
	s_nop 0
	global_load_lds_dwordx4 v172, s[4:5]
	s_add_i32 m0, s58, 0x2000
	s_nop 0
	global_load_lds_dwordx4 v182, s[4:5]
	v_lshl_add_u64 v[226:227], v[230:231], 0, s[36:37]
	s_mov_b32 m0, s63
	s_nop 0
	global_load_lds_dwordx4 v[226:227], off
	v_lshl_add_u64 v[226:227], v[232:233], 0, s[36:37]
	s_mov_b32 m0, s64
	s_nop 0
	global_load_lds_dwordx4 v[226:227], off
	s_waitcnt vmcnt(8)
	s_waitcnt lgkmcnt(0)
	s_barrier
	s_waitcnt lgkmcnt(0)
	v_mfma_f32_16x16x32_bf16 v[60:63], v[120:123], v[160:163], v[60:63]
	v_mfma_f32_16x16x32_bf16 v[56:59], v[128:131], v[160:163], v[56:59]
	v_mfma_f32_16x16x32_bf16 v[48:51], v[120:123], v[168:171], v[48:51]
	v_mfma_f32_16x16x32_bf16 v[40:43], v[128:131], v[168:171], v[40:43]
	v_mfma_f32_16x16x32_bf16 v[32:35], v[120:123], v[196:199], v[32:35]
	v_mfma_f32_16x16x32_bf16 v[24:27], v[128:131], v[196:199], v[24:27]
	v_mfma_f32_16x16x32_bf16 v[16:19], v[120:123], v[218:221], v[16:19]
	v_mfma_f32_16x16x32_bf16 v[8:11], v[128:131], v[218:221], v[8:11]
	v_mfma_f32_16x16x32_bf16 v[60:63], v[124:127], v[164:167], v[60:63]
	v_mfma_f32_16x16x32_bf16 v[56:59], v[132:135], v[164:167], v[56:59]
	v_mfma_f32_16x16x32_bf16 v[48:51], v[124:127], v[192:195], v[48:51]
	v_mfma_f32_16x16x32_bf16 v[40:43], v[132:135], v[192:195], v[40:43]
	v_mfma_f32_16x16x32_bf16 v[32:35], v[124:127], v[200:203], v[32:35]
	v_mfma_f32_16x16x32_bf16 v[24:27], v[132:135], v[200:203], v[24:27]
	v_mfma_f32_16x16x32_bf16 v[16:19], v[124:127], v[222:225], v[16:19]
	v_mfma_f32_16x16x32_bf16 v[8:11], v[132:135], v[222:225], v[8:11]
	v_mfma_f32_16x16x32_bf16 v[52:55], v[144:147], v[160:163], v[52:55]
	v_mfma_f32_16x16x32_bf16 v[44:47], v[152:155], v[160:163], v[44:47]
	v_mfma_f32_16x16x32_bf16 v[36:39], v[144:147], v[168:171], v[36:39]
	v_mfma_f32_16x16x32_bf16 v[28:31], v[152:155], v[168:171], v[28:31]
	v_mfma_f32_16x16x32_bf16 v[20:23], v[144:147], v[196:199], v[20:23]
	v_mfma_f32_16x16x32_bf16 v[12:15], v[152:155], v[196:199], v[12:15]
	v_mfma_f32_16x16x32_bf16 v[4:7], v[144:147], v[218:221], v[4:7]
	v_mfma_f32_16x16x32_bf16 v[0:3], v[152:155], v[218:221], v[0:3]
	v_mfma_f32_16x16x32_bf16 v[52:55], v[148:151], v[164:167], v[52:55]
	v_mfma_f32_16x16x32_bf16 v[44:47], v[156:159], v[164:167], v[44:47]
	v_mfma_f32_16x16x32_bf16 v[36:39], v[148:151], v[192:195], v[36:39]
	v_mfma_f32_16x16x32_bf16 v[28:31], v[156:159], v[192:195], v[28:31]
	v_mfma_f32_16x16x32_bf16 v[20:23], v[148:151], v[200:203], v[20:23]
	v_mfma_f32_16x16x32_bf16 v[12:15], v[156:159], v[200:203], v[12:15]
	v_mfma_f32_16x16x32_bf16 v[4:7], v[148:151], v[222:225], v[4:7]
	v_mfma_f32_16x16x32_bf16 v[0:3], v[156:159], v[222:225], v[0:3]
	s_barrier
	s_add_i32 s70, s70, 2
	s_add_u32 s56, s56, 0x100
	s_addc_u32 s57, s57, 0
	s_add_u32 s8, s8, 0x100
	s_addc_u32 s9, s9, 0
	s_cmp_gt_u32 s70, 13
	s_cbranch_scc0 .LBB0_914
	s_and_b64 vcc, exec, s[28:29]
	s_cbranch_vccz .LBB0_917
	s_barrier

.LBB0_934:
	s_add_u32 s4, s48, 0xfffc0080
	s_addc_u32 s5, s49, -1
	s_add_i32 s69, 0, 0x10000
	s_cmp_eq_u32 s68, 12
	s_cselect_b32 s5, s45, s5
	s_cselect_b32 s4, s66, s4
	s_cselect_b32 s57, s43, s9
	s_cselect_b32 s56, s67, s8
	s_add_i32 s72, 0, 0x14000
	v_add_u32_e32 v76, s69, v159
	v_add_u32_e32 v170, s72, v159
	ds_read_b128 v[64:67], v76
	ds_read_b128 v[68:71], v76 offset:1024
	ds_read_b128 v[72:75], v76 offset:2048
	ds_read_b128 v[76:79], v76 offset:3072
	ds_read_b128 v[154:157], v170
	ds_read_b128 v[162:165], v170 offset:1024
	ds_read_b128 v[166:169], v170 offset:2048
	ds_read_b128 v[182:185], v170 offset:3072
	s_add_i32 m0, s58, 0xc000
	ds_read_b128 v[186:189], v161
	ds_read_b128 v[190:193], v161 offset:1024
	ds_read_b128 v[194:197], v161 offset:2048
	ds_read_b128 v[198:201], v161 offset:3072
	ds_read_b128 v[214:217], v161 offset:4096
	ds_read_b128 v[218:221], v161 offset:5120
	ds_read_b128 v[222:225], v161 offset:6144
	ds_read_b128 v[226:229], v161 offset:7168
	global_load_lds_dwordx4 v150, s[48:49]
	s_add_i32 m0, s58, 0xe000
	s_nop 0
	global_load_lds_dwordx4 v152, s[48:49]
	s_waitcnt vmcnt(8)
	s_waitcnt lgkmcnt(0)
	s_barrier
	s_waitcnt lgkmcnt(0)
	v_mfma_f32_16x16x32_bf16 v[140:143], v[64:67], v[186:189], v[140:143]
	v_mfma_f32_16x16x32_bf16 v[136:139], v[72:75], v[186:189], v[136:139]
	v_mfma_f32_16x16x32_bf16 v[132:135], v[64:67], v[194:197], v[132:135]
	v_mfma_f32_16x16x32_bf16 v[128:131], v[72:75], v[194:197], v[128:131]
	v_mfma_f32_16x16x32_bf16 v[108:111], v[64:67], v[214:217], v[108:111]
	v_mfma_f32_16x16x32_bf16 v[104:107], v[72:75], v[214:217], v[104:107]
	v_mfma_f32_16x16x32_bf16 v[100:103], v[64:67], v[222:225], v[100:103]
	v_mfma_f32_16x16x32_bf16 v[96:99], v[72:75], v[222:225], v[96:99]
	v_mfma_f32_16x16x32_bf16 v[140:143], v[68:71], v[190:193], v[140:143]
	v_mfma_f32_16x16x32_bf16 v[136:139], v[76:79], v[190:193], v[136:139]
	v_mfma_f32_16x16x32_bf16 v[132:135], v[68:71], v[198:201], v[132:135]
	v_mfma_f32_16x16x32_bf16 v[128:131], v[76:79], v[198:201], v[128:131]
	v_mfma_f32_16x16x32_bf16 v[108:111], v[68:71], v[218:221], v[108:111]
	v_mfma_f32_16x16x32_bf16 v[104:107], v[76:79], v[218:221], v[104:107]
	v_mfma_f32_16x16x32_bf16 v[100:103], v[68:71], v[226:229], v[100:103]
	v_mfma_f32_16x16x32_bf16 v[96:99], v[76:79], v[226:229], v[96:99]
	v_mfma_f32_16x16x32_bf16 v[124:127], v[154:157], v[186:189], v[124:127]
	v_mfma_f32_16x16x32_bf16 v[120:123], v[166:169], v[186:189], v[120:123]
	v_mfma_f32_16x16x32_bf16 v[116:119], v[154:157], v[194:197], v[116:119]
	v_mfma_f32_16x16x32_bf16 v[112:115], v[166:169], v[194:197], v[112:115]
	v_mfma_f32_16x16x32_bf16 v[92:95], v[154:157], v[214:217], v[92:95]
	v_mfma_f32_16x16x32_bf16 v[88:91], v[166:169], v[214:217], v[88:91]
	v_mfma_f32_16x16x32_bf16 v[84:87], v[154:157], v[222:225], v[84:87]
	v_mfma_f32_16x16x32_bf16 v[80:83], v[166:169], v[222:225], v[80:83]
	v_mfma_f32_16x16x32_bf16 v[124:127], v[162:165], v[190:193], v[124:127]
	v_mfma_f32_16x16x32_bf16 v[120:123], v[182:185], v[190:193], v[120:123]
	v_mfma_f32_16x16x32_bf16 v[116:119], v[162:165], v[198:201], v[116:119]
	v_mfma_f32_16x16x32_bf16 v[112:115], v[182:185], v[198:201], v[112:115]
	v_mfma_f32_16x16x32_bf16 v[92:95], v[162:165], v[218:221], v[92:95]
	v_mfma_f32_16x16x32_bf16 v[88:91], v[182:185], v[218:221], v[88:91]
	v_mfma_f32_16x16x32_bf16 v[84:87], v[162:165], v[226:229], v[84:87]
	v_mfma_f32_16x16x32_bf16 v[80:83], v[182:185], v[226:229], v[80:83]
	s_barrier
	s_add_i32 s69, s69, s51
	v_lshl_add_u64 v[170:171], s[56:57], 0, v[172:173]
	s_mov_b32 m0, s69
	ds_read_b128 v[186:189], v161 offset:16384
	ds_read_b128 v[190:193], v161 offset:17408
	ds_read_b128 v[194:197], v161 offset:18432
	ds_read_b128 v[198:201], v161 offset:19456
	ds_read_b128 v[214:217], v161 offset:20480
	ds_read_b128 v[218:221], v161 offset:21504
	ds_read_b128 v[222:225], v161 offset:22528
	ds_read_b128 v[226:229], v161 offset:23552
	global_load_lds_dwordx4 v[170:171], off
	s_add_i32 m0, s69, 0x2000
	s_add_u32 s70, s56, 0x40000
	v_lshl_add_u64 v[202:203], s[56:57], 0, v[144:145]
	s_addc_u32 s71, s57, 0
	s_add_i32 s69, s72, s51
	global_load_lds_dwordx4 v[202:203], off
	s_mov_b32 m0, s69
	v_lshl_add_u64 v[232:233], s[4:5], 0, v[146:147]
	global_load_lds_dwordx4 v172, s[70:71]
	s_add_i32 m0, s69, 0x2000
	s_nop 0
	global_load_lds_dwordx4 v144, s[70:71]
	v_lshl_add_u64 v[230:231], s[4:5], 0, v[148:149]
	s_mov_b32 m0, s58
	s_nop 0
	global_load_lds_dwordx4 v[230:231], off
	s_mov_b32 m0, s59
	s_nop 0
	global_load_lds_dwordx4 v[232:233], off
	s_waitcnt vmcnt(8)
	s_waitcnt lgkmcnt(0)
	s_barrier
	s_waitcnt lgkmcnt(0)
	v_mfma_f32_16x16x32_bf16 v[60:63], v[64:67], v[186:189], v[60:63]
	v_mfma_f32_16x16x32_bf16 v[56:59], v[72:75], v[186:189], v[56:59]
	v_mfma_f32_16x16x32_bf16 v[52:55], v[64:67], v[194:197], v[52:55]
	v_mfma_f32_16x16x32_bf16 v[48:51], v[72:75], v[194:197], v[48:51]
	v_mfma_f32_16x16x32_bf16 v[28:31], v[64:67], v[214:217], v[28:31]
	v_mfma_f32_16x16x32_bf16 v[24:27], v[72:75], v[214:217], v[24:27]
	v_mfma_f32_16x16x32_bf16 v[20:23], v[64:67], v[222:225], v[20:23]
	v_mfma_f32_16x16x32_bf16 v[16:19], v[72:75], v[222:225], v[16:19]
	v_mfma_f32_16x16x32_bf16 v[60:63], v[68:71], v[190:193], v[60:63]
	v_mfma_f32_16x16x32_bf16 v[56:59], v[76:79], v[190:193], v[56:59]
	v_mfma_f32_16x16x32_bf16 v[52:55], v[68:71], v[198:201], v[52:55]
	v_mfma_f32_16x16x32_bf16 v[48:51], v[76:79], v[198:201], v[48:51]
	v_mfma_f32_16x16x32_bf16 v[28:31], v[68:71], v[218:221], v[28:31]
	v_mfma_f32_16x16x32_bf16 v[24:27], v[76:79], v[218:221], v[24:27]
	v_mfma_f32_16x16x32_bf16 v[20:23], v[68:71], v[226:229], v[20:23]
	v_mfma_f32_16x16x32_bf16 v[16:19], v[76:79], v[226:229], v[16:19]
	v_mfma_f32_16x16x32_bf16 v[44:47], v[154:157], v[186:189], v[44:47]
	v_mfma_f32_16x16x32_bf16 v[40:43], v[166:169], v[186:189], v[40:43]
	v_mfma_f32_16x16x32_bf16 v[36:39], v[154:157], v[194:197], v[36:39]
	v_mfma_f32_16x16x32_bf16 v[32:35], v[166:169], v[194:197], v[32:35]
	v_mfma_f32_16x16x32_bf16 v[12:15], v[154:157], v[214:217], v[12:15]
	v_mfma_f32_16x16x32_bf16 v[8:11], v[166:169], v[214:217], v[8:11]
	v_mfma_f32_16x16x32_bf16 v[4:7], v[154:157], v[222:225], v[4:7]
	v_mfma_f32_16x16x32_bf16 v[0:3], v[166:169], v[222:225], v[0:3]
	v_mfma_f32_16x16x32_bf16 v[44:47], v[162:165], v[190:193], v[44:47]
	v_mfma_f32_16x16x32_bf16 v[40:43], v[182:185], v[190:193], v[40:43]
	v_mfma_f32_16x16x32_bf16 v[36:39], v[162:165], v[198:201], v[36:39]
	v_mfma_f32_16x16x32_bf16 v[32:35], v[182:185], v[198:201], v[32:35]
	v_mfma_f32_16x16x32_bf16 v[12:15], v[162:165], v[218:221], v[12:15]
	v_mfma_f32_16x16x32_bf16 v[8:11], v[182:185], v[218:221], v[8:11]
	v_mfma_f32_16x16x32_bf16 v[4:7], v[162:165], v[226:229], v[4:7]
	v_mfma_f32_16x16x32_bf16 v[0:3], v[182:185], v[226:229], v[0:3]
	s_barrier
	s_add_i32 s69, 0, 0x18000
	s_add_i32 s70, 0, 0x1c000
	v_add_u32_e32 v76, s69, v159
	v_add_u32_e32 v182, s70, v159
	ds_read_b128 v[64:67], v76
	ds_read_b128 v[68:71], v76 offset:1024
	ds_read_b128 v[72:75], v76 offset:2048
	ds_read_b128 v[76:79], v76 offset:3072
	ds_read_b128 v[154:157], v182
	ds_read_b128 v[162:165], v182 offset:1024
	ds_read_b128 v[166:169], v182 offset:2048
	ds_read_b128 v[182:185], v182 offset:3072
	s_add_u32 s4, s4, 0x40000
	s_addc_u32 s5, s5, 0
	s_mov_b32 m0, s60
	ds_read_b128 v[186:189], v161 offset:32768
	ds_read_b128 v[190:193], v161 offset:33792
	ds_read_b128 v[194:197], v161 offset:34816
	ds_read_b128 v[198:201], v161 offset:35840
	ds_read_b128 v[214:217], v161 offset:36864
	ds_read_b128 v[218:221], v161 offset:37888
	ds_read_b128 v[222:225], v161 offset:38912
	ds_read_b128 v[226:229], v161 offset:39936
	global_load_lds_dwordx4 v148, s[4:5]
	s_mov_b32 m0, s61
	s_nop 0
	global_load_lds_dwordx4 v146, s[4:5]
	s_waitcnt vmcnt(8)
	s_waitcnt lgkmcnt(0)
	s_barrier
	s_waitcnt lgkmcnt(0)
	v_mfma_f32_16x16x32_bf16 v[140:143], v[64:67], v[186:189], v[140:143]
	v_mfma_f32_16x16x32_bf16 v[136:139], v[72:75], v[186:189], v[136:139]
	v_mfma_f32_16x16x32_bf16 v[132:135], v[64:67], v[194:197], v[132:135]
	v_mfma_f32_16x16x32_bf16 v[128:131], v[72:75], v[194:197], v[128:131]
	v_mfma_f32_16x16x32_bf16 v[108:111], v[64:67], v[214:217], v[108:111]
	v_mfma_f32_16x16x32_bf16 v[104:107], v[72:75], v[214:217], v[104:107]
	v_mfma_f32_16x16x32_bf16 v[100:103], v[64:67], v[222:225], v[100:103]
	v_mfma_f32_16x16x32_bf16 v[96:99], v[72:75], v[222:225], v[96:99]
	v_mfma_f32_16x16x32_bf16 v[140:143], v[68:71], v[190:193], v[140:143]
	v_mfma_f32_16x16x32_bf16 v[136:139], v[76:79], v[190:193], v[136:139]
	v_mfma_f32_16x16x32_bf16 v[132:135], v[68:71], v[198:201], v[132:135]
	v_mfma_f32_16x16x32_bf16 v[128:131], v[76:79], v[198:201], v[128:131]
	v_mfma_f32_16x16x32_bf16 v[108:111], v[68:71], v[218:221], v[108:111]
	v_mfma_f32_16x16x32_bf16 v[104:107], v[76:79], v[218:221], v[104:107]
	v_mfma_f32_16x16x32_bf16 v[100:103], v[68:71], v[226:229], v[100:103]
	v_mfma_f32_16x16x32_bf16 v[96:99], v[76:79], v[226:229], v[96:99]
	v_mfma_f32_16x16x32_bf16 v[124:127], v[154:157], v[186:189], v[124:127]
	v_mfma_f32_16x16x32_bf16 v[120:123], v[166:169], v[186:189], v[120:123]
	v_mfma_f32_16x16x32_bf16 v[116:119], v[154:157], v[194:197], v[116:119]
	v_mfma_f32_16x16x32_bf16 v[112:115], v[166:169], v[194:197], v[112:115]
	v_mfma_f32_16x16x32_bf16 v[92:95], v[154:157], v[214:217], v[92:95]
	v_mfma_f32_16x16x32_bf16 v[88:91], v[166:169], v[214:217], v[88:91]
	v_mfma_f32_16x16x32_bf16 v[84:87], v[154:157], v[222:225], v[84:87]
	v_mfma_f32_16x16x32_bf16 v[80:83], v[166:169], v[222:225], v[80:83]
	v_mfma_f32_16x16x32_bf16 v[124:127], v[162:165], v[190:193], v[124:127]
	v_mfma_f32_16x16x32_bf16 v[120:123], v[182:185], v[190:193], v[120:123]
	v_mfma_f32_16x16x32_bf16 v[116:119], v[162:165], v[198:201], v[116:119]
	v_mfma_f32_16x16x32_bf16 v[112:115], v[182:185], v[198:201], v[112:115]
	v_mfma_f32_16x16x32_bf16 v[92:95], v[162:165], v[218:221], v[92:95]
	v_mfma_f32_16x16x32_bf16 v[88:91], v[182:185], v[218:221], v[88:91]
	v_mfma_f32_16x16x32_bf16 v[84:87], v[162:165], v[226:229], v[84:87]
	v_mfma_f32_16x16x32_bf16 v[80:83], v[182:185], v[226:229], v[80:83]
	s_barrier
	s_add_i32 s4, s69, s51
	v_lshl_add_u64 v[170:171], v[170:171], 0, s[36:37]
	s_mov_b32 m0, s4
	ds_read_b128 v[186:189], v161 offset:49152
	ds_read_b128 v[190:193], v161 offset:50176
	ds_read_b128 v[194:197], v161 offset:51200
	ds_read_b128 v[198:201], v161 offset:52224
	ds_read_b128 v[214:217], v161 offset:53248
	ds_read_b128 v[218:221], v161 offset:54272
	ds_read_b128 v[222:225], v161 offset:55296
	ds_read_b128 v[226:229], v161 offset:56320
	global_load_lds_dwordx4 v[170:171], off
	s_add_i32 m0, s4, 0x2000
	s_add_u32 s4, s56, 0x40080
	v_lshl_add_u64 v[170:171], v[202:203], 0, s[36:37]
	s_addc_u32 s5, s57, 0
	s_add_i32 s56, s70, s51
	global_load_lds_dwordx4 v[170:171], off
	s_mov_b32 m0, s56
	s_nop 0
	global_load_lds_dwordx4 v172, s[4:5]
	s_add_i32 m0, s56, 0x2000
	s_nop 0
	global_load_lds_dwordx4 v144, s[4:5]
	v_lshl_add_u64 v[170:171], v[230:231], 0, s[36:37]
	s_mov_b32 m0, s62
	s_nop 0
	global_load_lds_dwordx4 v[170:171], off
	v_lshl_add_u64 v[170:171], v[232:233], 0, s[36:37]
	s_mov_b32 m0, s63
	s_nop 0
	global_load_lds_dwordx4 v[170:171], off
	s_waitcnt vmcnt(8)
	s_waitcnt lgkmcnt(0)
	s_barrier
	s_waitcnt lgkmcnt(0)
	v_mfma_f32_16x16x32_bf16 v[60:63], v[64:67], v[186:189], v[60:63]
	v_mfma_f32_16x16x32_bf16 v[56:59], v[72:75], v[186:189], v[56:59]
	v_mfma_f32_16x16x32_bf16 v[52:55], v[64:67], v[194:197], v[52:55]
	v_mfma_f32_16x16x32_bf16 v[48:51], v[72:75], v[194:197], v[48:51]
	v_mfma_f32_16x16x32_bf16 v[28:31], v[64:67], v[214:217], v[28:31]
	v_mfma_f32_16x16x32_bf16 v[24:27], v[72:75], v[214:217], v[24:27]
	v_mfma_f32_16x16x32_bf16 v[20:23], v[64:67], v[222:225], v[20:23]
	v_mfma_f32_16x16x32_bf16 v[16:19], v[72:75], v[222:225], v[16:19]
	v_mfma_f32_16x16x32_bf16 v[60:63], v[68:71], v[190:193], v[60:63]
	v_mfma_f32_16x16x32_bf16 v[56:59], v[76:79], v[190:193], v[56:59]
	v_mfma_f32_16x16x32_bf16 v[52:55], v[68:71], v[198:201], v[52:55]
	v_mfma_f32_16x16x32_bf16 v[48:51], v[76:79], v[198:201], v[48:51]
	v_mfma_f32_16x16x32_bf16 v[28:31], v[68:71], v[218:221], v[28:31]
	v_mfma_f32_16x16x32_bf16 v[24:27], v[76:79], v[218:221], v[24:27]
	v_mfma_f32_16x16x32_bf16 v[20:23], v[68:71], v[226:229], v[20:23]
	v_mfma_f32_16x16x32_bf16 v[16:19], v[76:79], v[226:229], v[16:19]
	v_mfma_f32_16x16x32_bf16 v[44:47], v[154:157], v[186:189], v[44:47]
	v_mfma_f32_16x16x32_bf16 v[40:43], v[166:169], v[186:189], v[40:43]
	v_mfma_f32_16x16x32_bf16 v[36:39], v[154:157], v[194:197], v[36:39]
	v_mfma_f32_16x16x32_bf16 v[32:35], v[166:169], v[194:197], v[32:35]
	v_mfma_f32_16x16x32_bf16 v[12:15], v[154:157], v[214:217], v[12:15]
	v_mfma_f32_16x16x32_bf16 v[8:11], v[166:169], v[214:217], v[8:11]
	v_mfma_f32_16x16x32_bf16 v[4:7], v[154:157], v[222:225], v[4:7]
	v_mfma_f32_16x16x32_bf16 v[0:3], v[166:169], v[222:225], v[0:3]
	v_mfma_f32_16x16x32_bf16 v[44:47], v[162:165], v[190:193], v[44:47]
	v_mfma_f32_16x16x32_bf16 v[40:43], v[182:185], v[190:193], v[40:43]
	v_mfma_f32_16x16x32_bf16 v[36:39], v[162:165], v[198:201], v[36:39]
	v_mfma_f32_16x16x32_bf16 v[32:35], v[182:185], v[198:201], v[32:35]
	v_mfma_f32_16x16x32_bf16 v[12:15], v[162:165], v[218:221], v[12:15]
	v_mfma_f32_16x16x32_bf16 v[8:11], v[182:185], v[218:221], v[8:11]
	v_mfma_f32_16x16x32_bf16 v[4:7], v[162:165], v[226:229], v[4:7]
	v_mfma_f32_16x16x32_bf16 v[0:3], v[182:185], v[226:229], v[0:3]
	s_barrier
	s_add_i32 s68, s68, 2
	s_add_u32 s48, s48, 0x100
	s_addc_u32 s49, s49, 0
	s_add_u32 s8, s8, 0x100
	s_addc_u32 s9, s9, 0
	s_cmp_gt_u32 s68, 13
	s_cbranch_scc0 .LBB0_934
	s_and_b64 vcc, exec, s[38:39]
	s_cbranch_vccz .LBB0_937
	s_barrier

.LBB0_1154:
	s_add_u32 s4, s56, 0xfffc0080
	s_addc_u32 s5, s57, -1
	s_add_i32 s75, 0, 0x10000
	s_cmp_eq_u32 s74, 12
	s_cselect_b32 s5, s47, s5
	s_cselect_b32 s4, s70, s4
	v_add_u32_e32 v138, s75, v141
	s_cselect_b32 s59, s45, s73
	s_cselect_b32 s58, s71, s72
	s_add_i32 s77, 0, 0x14000
	ds_read_b128 v[144:147], v138
	ds_read_b128 v[148:151], v138 offset:1024
	ds_read_b128 v[152:155], v138 offset:2048
	ds_read_b128 v[156:159], v138 offset:3072
	v_add_u32_e32 v138, s77, v141
	ds_read_b128 v[160:163], v138
	ds_read_b128 v[164:167], v138 offset:1024
	ds_read_b128 v[168:171], v138 offset:2048
	ds_read_b128 v[182:185], v138 offset:3072
	s_add_i32 m0, s51, 0xc000
	ds_read_b128 v[186:189], v143
	ds_read_b128 v[190:193], v143 offset:1024
	ds_read_b128 v[194:197], v143 offset:2048
	ds_read_b128 v[198:201], v143 offset:3072
	ds_read_b128 v[214:217], v143 offset:4096
	ds_read_b128 v[218:221], v143 offset:5120
	ds_read_b128 v[222:225], v143 offset:6144
	ds_read_b128 v[226:229], v143 offset:7168
	global_load_lds_dwordx4 v134, s[56:57]
	s_add_i32 m0, s51, 0xe000
	s_nop 0
	global_load_lds_dwordx4 v136, s[56:57]
	s_waitcnt vmcnt(8)
	s_waitcnt lgkmcnt(0)
	s_barrier
	s_waitcnt lgkmcnt(0)
	v_mfma_f32_16x16x32_bf16 v[124:127], v[144:147], v[186:189], v[124:127]
	v_mfma_f32_16x16x32_bf16 v[120:123], v[152:155], v[186:189], v[120:123]
	v_mfma_f32_16x16x32_bf16 v[116:119], v[144:147], v[194:197], v[116:119]
	v_mfma_f32_16x16x32_bf16 v[108:111], v[152:155], v[194:197], v[108:111]
	v_mfma_f32_16x16x32_bf16 v[100:103], v[144:147], v[214:217], v[100:103]
	v_mfma_f32_16x16x32_bf16 v[92:95], v[152:155], v[214:217], v[92:95]
	v_mfma_f32_16x16x32_bf16 v[84:87], v[144:147], v[222:225], v[84:87]
	v_mfma_f32_16x16x32_bf16 v[76:79], v[152:155], v[222:225], v[76:79]
	v_mfma_f32_16x16x32_bf16 v[124:127], v[148:151], v[190:193], v[124:127]
	v_mfma_f32_16x16x32_bf16 v[120:123], v[156:159], v[190:193], v[120:123]
	v_mfma_f32_16x16x32_bf16 v[116:119], v[148:151], v[198:201], v[116:119]
	v_mfma_f32_16x16x32_bf16 v[108:111], v[156:159], v[198:201], v[108:111]
	v_mfma_f32_16x16x32_bf16 v[100:103], v[148:151], v[218:221], v[100:103]
	v_mfma_f32_16x16x32_bf16 v[92:95], v[156:159], v[218:221], v[92:95]
	v_mfma_f32_16x16x32_bf16 v[84:87], v[148:151], v[226:229], v[84:87]
	v_mfma_f32_16x16x32_bf16 v[76:79], v[156:159], v[226:229], v[76:79]
	v_mfma_f32_16x16x32_bf16 v[112:115], v[160:163], v[186:189], v[112:115]
	v_mfma_f32_16x16x32_bf16 v[104:107], v[168:171], v[186:189], v[104:107]
	v_mfma_f32_16x16x32_bf16 v[96:99], v[160:163], v[194:197], v[96:99]
	v_mfma_f32_16x16x32_bf16 v[88:91], v[168:171], v[194:197], v[88:91]
	v_mfma_f32_16x16x32_bf16 v[80:83], v[160:163], v[214:217], v[80:83]
	v_mfma_f32_16x16x32_bf16 v[72:75], v[168:171], v[214:217], v[72:75]
	v_mfma_f32_16x16x32_bf16 v[68:71], v[160:163], v[222:225], v[68:71]
	v_mfma_f32_16x16x32_bf16 v[64:67], v[168:171], v[222:225], v[64:67]
	v_mfma_f32_16x16x32_bf16 v[112:115], v[164:167], v[190:193], v[112:115]
	v_mfma_f32_16x16x32_bf16 v[104:107], v[182:185], v[190:193], v[104:107]
	v_mfma_f32_16x16x32_bf16 v[96:99], v[164:167], v[198:201], v[96:99]
	v_mfma_f32_16x16x32_bf16 v[88:91], v[182:185], v[198:201], v[88:91]
	v_mfma_f32_16x16x32_bf16 v[80:83], v[164:167], v[218:221], v[80:83]
	v_mfma_f32_16x16x32_bf16 v[72:75], v[182:185], v[218:221], v[72:75]
	v_mfma_f32_16x16x32_bf16 v[68:71], v[164:167], v[226:229], v[68:71]
	v_mfma_f32_16x16x32_bf16 v[64:67], v[182:185], v[226:229], v[64:67]
	s_barrier
	s_add_i32 s75, s75, s63
	v_lshl_add_u64 v[138:139], s[58:59], 0, v[172:173]
	s_mov_b32 m0, s75
	ds_read_b128 v[186:189], v143 offset:16384
	ds_read_b128 v[190:193], v143 offset:17408
	ds_read_b128 v[194:197], v143 offset:18432
	ds_read_b128 v[198:201], v143 offset:19456
	ds_read_b128 v[214:217], v143 offset:20480
	ds_read_b128 v[218:221], v143 offset:21504
	ds_read_b128 v[222:225], v143 offset:22528
	ds_read_b128 v[226:229], v143 offset:23552
	global_load_lds_dwordx4 v[138:139], off
	s_add_i32 m0, s75, 0x2000
	s_add_u32 s78, s58, 0x40000
	v_lshl_add_u64 v[202:203], s[58:59], 0, v[128:129]
	s_addc_u32 s79, s59, 0
	s_add_i32 s75, s77, s63
	global_load_lds_dwordx4 v[202:203], off
	s_mov_b32 m0, s75
	v_lshl_add_u64 v[232:233], s[4:5], 0, v[130:131]
	global_load_lds_dwordx4 v172, s[78:79]
	s_add_i32 m0, s75, 0x2000
	s_nop 0
	global_load_lds_dwordx4 v128, s[78:79]
	v_lshl_add_u64 v[230:231], s[4:5], 0, v[132:133]
	s_mov_b32 m0, s51
	s_nop 0
	global_load_lds_dwordx4 v[230:231], off
	s_mov_b32 m0, s53
	s_nop 0
	global_load_lds_dwordx4 v[232:233], off
	s_waitcnt vmcnt(8)
	s_waitcnt lgkmcnt(0)
	s_barrier
	s_waitcnt lgkmcnt(0)
	v_mfma_f32_16x16x32_bf16 v[60:63], v[144:147], v[186:189], v[60:63]
	v_mfma_f32_16x16x32_bf16 v[56:59], v[152:155], v[186:189], v[56:59]
	v_mfma_f32_16x16x32_bf16 v[52:55], v[144:147], v[194:197], v[52:55]
	v_mfma_f32_16x16x32_bf16 v[44:47], v[152:155], v[194:197], v[44:47]
	v_mfma_f32_16x16x32_bf16 v[36:39], v[144:147], v[214:217], v[36:39]
	v_mfma_f32_16x16x32_bf16 v[28:31], v[152:155], v[214:217], v[28:31]
	v_mfma_f32_16x16x32_bf16 v[20:23], v[144:147], v[222:225], v[20:23]
	v_mfma_f32_16x16x32_bf16 v[12:15], v[152:155], v[222:225], v[12:15]
	v_mfma_f32_16x16x32_bf16 v[60:63], v[148:151], v[190:193], v[60:63]
	v_mfma_f32_16x16x32_bf16 v[56:59], v[156:159], v[190:193], v[56:59]
	v_mfma_f32_16x16x32_bf16 v[52:55], v[148:151], v[198:201], v[52:55]
	v_mfma_f32_16x16x32_bf16 v[44:47], v[156:159], v[198:201], v[44:47]
	v_mfma_f32_16x16x32_bf16 v[36:39], v[148:151], v[218:221], v[36:39]
	v_mfma_f32_16x16x32_bf16 v[28:31], v[156:159], v[218:221], v[28:31]
	v_mfma_f32_16x16x32_bf16 v[20:23], v[148:151], v[226:229], v[20:23]
	v_mfma_f32_16x16x32_bf16 v[12:15], v[156:159], v[226:229], v[12:15]
	v_mfma_f32_16x16x32_bf16 v[48:51], v[160:163], v[186:189], v[48:51]
	v_mfma_f32_16x16x32_bf16 v[40:43], v[168:171], v[186:189], v[40:43]
	v_mfma_f32_16x16x32_bf16 v[32:35], v[160:163], v[194:197], v[32:35]
	v_mfma_f32_16x16x32_bf16 v[24:27], v[168:171], v[194:197], v[24:27]
	v_mfma_f32_16x16x32_bf16 v[16:19], v[160:163], v[214:217], v[16:19]
	v_mfma_f32_16x16x32_bf16 v[8:11], v[168:171], v[214:217], v[8:11]
	v_mfma_f32_16x16x32_bf16 v[4:7], v[160:163], v[222:225], v[4:7]
	v_mfma_f32_16x16x32_bf16 v[0:3], v[168:171], v[222:225], v[0:3]
	v_mfma_f32_16x16x32_bf16 v[48:51], v[164:167], v[190:193], v[48:51]
	v_mfma_f32_16x16x32_bf16 v[40:43], v[182:185], v[190:193], v[40:43]
	v_mfma_f32_16x16x32_bf16 v[32:35], v[164:167], v[198:201], v[32:35]
	v_mfma_f32_16x16x32_bf16 v[24:27], v[182:185], v[198:201], v[24:27]
	v_mfma_f32_16x16x32_bf16 v[16:19], v[164:167], v[218:221], v[16:19]
	v_mfma_f32_16x16x32_bf16 v[8:11], v[182:185], v[218:221], v[8:11]
	v_mfma_f32_16x16x32_bf16 v[4:7], v[164:167], v[226:229], v[4:7]
	v_mfma_f32_16x16x32_bf16 v[0:3], v[182:185], v[226:229], v[0:3]
	s_barrier
	s_add_i32 s75, 0, 0x18000
	s_add_i32 s77, 0, 0x1c000
	v_add_u32_e32 v156, s75, v141
	v_add_u32_e32 v182, s77, v141
	ds_read_b128 v[144:147], v156
	ds_read_b128 v[148:151], v156 offset:1024
	ds_read_b128 v[152:155], v156 offset:2048
	ds_read_b128 v[156:159], v156 offset:3072
	ds_read_b128 v[160:163], v182
	ds_read_b128 v[164:167], v182 offset:1024
	ds_read_b128 v[168:171], v182 offset:2048
	ds_read_b128 v[182:185], v182 offset:3072
	s_add_u32 s4, s4, 0x40000
	s_addc_u32 s5, s5, 0
	s_mov_b32 m0, s65
	ds_read_b128 v[186:189], v143 offset:32768
	ds_read_b128 v[190:193], v143 offset:33792
	ds_read_b128 v[194:197], v143 offset:34816
	ds_read_b128 v[198:201], v143 offset:35840
	ds_read_b128 v[214:217], v143 offset:36864
	ds_read_b128 v[218:221], v143 offset:37888
	ds_read_b128 v[222:225], v143 offset:38912
	ds_read_b128 v[226:229], v143 offset:39936
	global_load_lds_dwordx4 v132, s[4:5]
	s_mov_b32 m0, s66
	s_nop 0
	global_load_lds_dwordx4 v130, s[4:5]
	s_waitcnt vmcnt(8)
	s_waitcnt lgkmcnt(0)
	s_barrier
	s_waitcnt lgkmcnt(0)
	v_mfma_f32_16x16x32_bf16 v[124:127], v[144:147], v[186:189], v[124:127]
	v_mfma_f32_16x16x32_bf16 v[120:123], v[152:155], v[186:189], v[120:123]
	v_mfma_f32_16x16x32_bf16 v[116:119], v[144:147], v[194:197], v[116:119]
	v_mfma_f32_16x16x32_bf16 v[108:111], v[152:155], v[194:197], v[108:111]
	v_mfma_f32_16x16x32_bf16 v[100:103], v[144:147], v[214:217], v[100:103]
	v_mfma_f32_16x16x32_bf16 v[92:95], v[152:155], v[214:217], v[92:95]
	v_mfma_f32_16x16x32_bf16 v[84:87], v[144:147], v[222:225], v[84:87]
	v_mfma_f32_16x16x32_bf16 v[76:79], v[152:155], v[222:225], v[76:79]
	v_mfma_f32_16x16x32_bf16 v[124:127], v[148:151], v[190:193], v[124:127]
	v_mfma_f32_16x16x32_bf16 v[120:123], v[156:159], v[190:193], v[120:123]
	v_mfma_f32_16x16x32_bf16 v[116:119], v[148:151], v[198:201], v[116:119]
	v_mfma_f32_16x16x32_bf16 v[108:111], v[156:159], v[198:201], v[108:111]
	v_mfma_f32_16x16x32_bf16 v[100:103], v[148:151], v[218:221], v[100:103]
	v_mfma_f32_16x16x32_bf16 v[92:95], v[156:159], v[218:221], v[92:95]
	v_mfma_f32_16x16x32_bf16 v[84:87], v[148:151], v[226:229], v[84:87]
	v_mfma_f32_16x16x32_bf16 v[76:79], v[156:159], v[226:229], v[76:79]
	v_mfma_f32_16x16x32_bf16 v[112:115], v[160:163], v[186:189], v[112:115]
	v_mfma_f32_16x16x32_bf16 v[104:107], v[168:171], v[186:189], v[104:107]
	v_mfma_f32_16x16x32_bf16 v[96:99], v[160:163], v[194:197], v[96:99]
	v_mfma_f32_16x16x32_bf16 v[88:91], v[168:171], v[194:197], v[88:91]
	v_mfma_f32_16x16x32_bf16 v[80:83], v[160:163], v[214:217], v[80:83]
	v_mfma_f32_16x16x32_bf16 v[72:75], v[168:171], v[214:217], v[72:75]
	v_mfma_f32_16x16x32_bf16 v[68:71], v[160:163], v[222:225], v[68:71]
	v_mfma_f32_16x16x32_bf16 v[64:67], v[168:171], v[222:225], v[64:67]
	v_mfma_f32_16x16x32_bf16 v[112:115], v[164:167], v[190:193], v[112:115]
	v_mfma_f32_16x16x32_bf16 v[104:107], v[182:185], v[190:193], v[104:107]
	v_mfma_f32_16x16x32_bf16 v[96:99], v[164:167], v[198:201], v[96:99]
	v_mfma_f32_16x16x32_bf16 v[88:91], v[182:185], v[198:201], v[88:91]
	v_mfma_f32_16x16x32_bf16 v[80:83], v[164:167], v[218:221], v[80:83]
	v_mfma_f32_16x16x32_bf16 v[72:75], v[182:185], v[218:221], v[72:75]
	v_mfma_f32_16x16x32_bf16 v[68:71], v[164:167], v[226:229], v[68:71]
	v_mfma_f32_16x16x32_bf16 v[64:67], v[182:185], v[226:229], v[64:67]
	s_barrier
	s_add_i32 s4, s75, s63
	v_lshl_add_u64 v[138:139], v[138:139], 0, s[36:37]
	s_mov_b32 m0, s4
	ds_read_b128 v[186:189], v143 offset:49152
	ds_read_b128 v[190:193], v143 offset:50176
	ds_read_b128 v[194:197], v143 offset:51200
	ds_read_b128 v[198:201], v143 offset:52224
	ds_read_b128 v[214:217], v143 offset:53248
	ds_read_b128 v[218:221], v143 offset:54272
	ds_read_b128 v[222:225], v143 offset:55296
	ds_read_b128 v[226:229], v143 offset:56320
	global_load_lds_dwordx4 v[138:139], off
	s_add_i32 m0, s4, 0x2000
	s_add_u32 s4, s58, 0x40080
	v_lshl_add_u64 v[138:139], v[202:203], 0, s[36:37]
	s_addc_u32 s5, s59, 0
	s_add_i32 s58, s77, s63
	global_load_lds_dwordx4 v[138:139], off
	s_mov_b32 m0, s58
	s_nop 0
	global_load_lds_dwordx4 v172, s[4:5]
	s_add_i32 m0, s58, 0x2000
	s_nop 0
	global_load_lds_dwordx4 v128, s[4:5]
	v_lshl_add_u64 v[138:139], v[230:231], 0, s[36:37]
	s_mov_b32 m0, s67
	s_nop 0
	global_load_lds_dwordx4 v[138:139], off
	v_lshl_add_u64 v[138:139], v[232:233], 0, s[36:37]
	s_mov_b32 m0, s68
	s_nop 0
	global_load_lds_dwordx4 v[138:139], off
	s_waitcnt vmcnt(8)
	s_waitcnt lgkmcnt(0)
	s_barrier
	s_waitcnt lgkmcnt(0)
	v_mfma_f32_16x16x32_bf16 v[60:63], v[144:147], v[186:189], v[60:63]
	v_mfma_f32_16x16x32_bf16 v[56:59], v[152:155], v[186:189], v[56:59]
	v_mfma_f32_16x16x32_bf16 v[52:55], v[144:147], v[194:197], v[52:55]
	v_mfma_f32_16x16x32_bf16 v[44:47], v[152:155], v[194:197], v[44:47]
	v_mfma_f32_16x16x32_bf16 v[36:39], v[144:147], v[214:217], v[36:39]
	v_mfma_f32_16x16x32_bf16 v[28:31], v[152:155], v[214:217], v[28:31]
	v_mfma_f32_16x16x32_bf16 v[20:23], v[144:147], v[222:225], v[20:23]
	v_mfma_f32_16x16x32_bf16 v[12:15], v[152:155], v[222:225], v[12:15]
	v_mfma_f32_16x16x32_bf16 v[60:63], v[148:151], v[190:193], v[60:63]
	v_mfma_f32_16x16x32_bf16 v[56:59], v[156:159], v[190:193], v[56:59]
	v_mfma_f32_16x16x32_bf16 v[52:55], v[148:151], v[198:201], v[52:55]
	v_mfma_f32_16x16x32_bf16 v[44:47], v[156:159], v[198:201], v[44:47]
	v_mfma_f32_16x16x32_bf16 v[36:39], v[148:151], v[218:221], v[36:39]
	v_mfma_f32_16x16x32_bf16 v[28:31], v[156:159], v[218:221], v[28:31]
	v_mfma_f32_16x16x32_bf16 v[20:23], v[148:151], v[226:229], v[20:23]
	v_mfma_f32_16x16x32_bf16 v[12:15], v[156:159], v[226:229], v[12:15]
	v_mfma_f32_16x16x32_bf16 v[48:51], v[160:163], v[186:189], v[48:51]
	v_mfma_f32_16x16x32_bf16 v[40:43], v[168:171], v[186:189], v[40:43]
	v_mfma_f32_16x16x32_bf16 v[32:35], v[160:163], v[194:197], v[32:35]
	v_mfma_f32_16x16x32_bf16 v[24:27], v[168:171], v[194:197], v[24:27]
	v_mfma_f32_16x16x32_bf16 v[16:19], v[160:163], v[214:217], v[16:19]
	v_mfma_f32_16x16x32_bf16 v[8:11], v[168:171], v[214:217], v[8:11]
	v_mfma_f32_16x16x32_bf16 v[4:7], v[160:163], v[222:225], v[4:7]
	v_mfma_f32_16x16x32_bf16 v[0:3], v[168:171], v[222:225], v[0:3]
	v_mfma_f32_16x16x32_bf16 v[48:51], v[164:167], v[190:193], v[48:51]
	v_mfma_f32_16x16x32_bf16 v[40:43], v[182:185], v[190:193], v[40:43]
	v_mfma_f32_16x16x32_bf16 v[32:35], v[164:167], v[198:201], v[32:35]
	v_mfma_f32_16x16x32_bf16 v[24:27], v[182:185], v[198:201], v[24:27]
	v_mfma_f32_16x16x32_bf16 v[16:19], v[164:167], v[218:221], v[16:19]
	v_mfma_f32_16x16x32_bf16 v[8:11], v[182:185], v[218:221], v[8:11]
	v_mfma_f32_16x16x32_bf16 v[4:7], v[164:167], v[226:229], v[4:7]
	v_mfma_f32_16x16x32_bf16 v[0:3], v[182:185], v[226:229], v[0:3]
	s_barrier
	s_add_i32 s74, s74, 2
	s_add_u32 s56, s56, 0x100
	s_addc_u32 s57, s57, 0
	s_add_u32 s72, s72, 0x100
	s_addc_u32 s73, s73, 0
	s_cmp_gt_u32 s74, 13
	s_cbranch_scc0 .LBB0_1154
	s_and_b64 vcc, exec, s[40:41]
	s_cbranch_vccz .LBB0_1157
	s_barrier

.LBB0_1412:
	s_add_i32 s63, s4, 2
	s_add_u32 s64, s46, 0x80
	s_addc_u32 s5, s47, 0
	s_add_i32 s66, 0, 0x10000
	s_cmp_eq_u32 s55, s4
	s_cselect_b32 s5, s41, s5
	s_cselect_b32 s4, s40, s64
	s_cselect_b32 s65, s45, s49
	s_cselect_b32 s64, s44, s48
	s_add_i32 s67, 0, 0x14000
	v_add_u32_e32 v132, s66, v215
	v_add_u32_e32 v156, s67, v215
	ds_read_b128 v[120:123], v132
	ds_read_b128 v[124:127], v132 offset:1024
	ds_read_b128 v[128:131], v132 offset:2048
	ds_read_b128 v[132:135], v132 offset:3072
	ds_read_b128 v[144:147], v156
	ds_read_b128 v[148:151], v156 offset:1024
	ds_read_b128 v[152:155], v156 offset:2048
	ds_read_b128 v[156:159], v156 offset:3072
	s_add_i32 m0, s51, 0xc000
	ds_read_b128 v[160:163], v217
	ds_read_b128 v[164:167], v217 offset:1024
	ds_read_b128 v[168:171], v217 offset:2048
	ds_read_b128 v[192:195], v217 offset:3072
	ds_read_b128 v[196:199], v217 offset:4096
	ds_read_b128 v[200:203], v217 offset:5120
	ds_read_b128 v[218:221], v217 offset:6144
	ds_read_b128 v[222:225], v217 offset:7168
	global_load_lds_dwordx4 v188, s[46:47]
	s_add_i32 m0, s51, 0xe000
	s_nop 0
	global_load_lds_dwordx4 v190, s[46:47]
	s_waitcnt vmcnt(8)
	s_waitcnt lgkmcnt(0)
	s_barrier
	s_waitcnt lgkmcnt(0)
	v_mfma_f32_16x16x32_bf16 v[140:143], v[120:123], v[160:163], v[140:143]
	v_mfma_f32_16x16x32_bf16 v[136:139], v[128:131], v[160:163], v[136:139]
	v_mfma_f32_16x16x32_bf16 v[108:111], v[120:123], v[168:171], v[108:111]
	v_mfma_f32_16x16x32_bf16 v[104:107], v[128:131], v[168:171], v[104:107]
	v_mfma_f32_16x16x32_bf16 v[96:99], v[120:123], v[196:199], v[96:99]
	v_mfma_f32_16x16x32_bf16 v[88:91], v[128:131], v[196:199], v[88:91]
	v_mfma_f32_16x16x32_bf16 v[80:83], v[120:123], v[218:221], v[80:83]
	v_mfma_f32_16x16x32_bf16 v[72:75], v[128:131], v[218:221], v[72:75]
	v_mfma_f32_16x16x32_bf16 v[140:143], v[124:127], v[164:167], v[140:143]
	v_mfma_f32_16x16x32_bf16 v[136:139], v[132:135], v[164:167], v[136:139]
	v_mfma_f32_16x16x32_bf16 v[108:111], v[124:127], v[192:195], v[108:111]
	v_mfma_f32_16x16x32_bf16 v[104:107], v[132:135], v[192:195], v[104:107]
	v_mfma_f32_16x16x32_bf16 v[96:99], v[124:127], v[200:203], v[96:99]
	v_mfma_f32_16x16x32_bf16 v[88:91], v[132:135], v[200:203], v[88:91]
	v_mfma_f32_16x16x32_bf16 v[80:83], v[124:127], v[222:225], v[80:83]
	v_mfma_f32_16x16x32_bf16 v[72:75], v[132:135], v[222:225], v[72:75]
	v_mfma_f32_16x16x32_bf16 v[116:119], v[144:147], v[160:163], v[116:119]
	v_mfma_f32_16x16x32_bf16 v[112:115], v[152:155], v[160:163], v[112:115]
	v_mfma_f32_16x16x32_bf16 v[100:103], v[144:147], v[168:171], v[100:103]
	v_mfma_f32_16x16x32_bf16 v[92:95], v[152:155], v[168:171], v[92:95]
	v_mfma_f32_16x16x32_bf16 v[84:87], v[144:147], v[196:199], v[84:87]
	v_mfma_f32_16x16x32_bf16 v[76:79], v[152:155], v[196:199], v[76:79]
	v_mfma_f32_16x16x32_bf16 v[68:71], v[144:147], v[218:221], v[68:71]
	v_mfma_f32_16x16x32_bf16 v[64:67], v[152:155], v[218:221], v[64:67]
	v_mfma_f32_16x16x32_bf16 v[116:119], v[148:151], v[164:167], v[116:119]
	v_mfma_f32_16x16x32_bf16 v[112:115], v[156:159], v[164:167], v[112:115]
	v_mfma_f32_16x16x32_bf16 v[100:103], v[148:151], v[192:195], v[100:103]
	v_mfma_f32_16x16x32_bf16 v[92:95], v[156:159], v[192:195], v[92:95]
	v_mfma_f32_16x16x32_bf16 v[84:87], v[148:151], v[200:203], v[84:87]
	v_mfma_f32_16x16x32_bf16 v[76:79], v[156:159], v[200:203], v[76:79]
	v_mfma_f32_16x16x32_bf16 v[68:71], v[148:151], v[222:225], v[68:71]
	v_mfma_f32_16x16x32_bf16 v[64:67], v[156:159], v[222:225], v[64:67]
	s_barrier
	s_add_i32 s66, s66, s50
	v_lshl_add_u64 v[226:227], s[64:65], 0, v[172:173]
	s_mov_b32 m0, s66
	ds_read_b128 v[160:163], v217 offset:16384
	ds_read_b128 v[164:167], v217 offset:17408
	ds_read_b128 v[168:171], v217 offset:18432
	ds_read_b128 v[192:195], v217 offset:19456
	ds_read_b128 v[196:199], v217 offset:20480
	ds_read_b128 v[200:203], v217 offset:21504
	ds_read_b128 v[218:221], v217 offset:22528
	ds_read_b128 v[222:225], v217 offset:23552
	global_load_lds_dwordx4 v[226:227], off
	s_add_i32 m0, s66, 0x2000
	v_lshl_add_u64 v[228:229], s[64:65], 0, v[182:183]
	s_add_u32 s64, s64, s26
	s_addc_u32 s65, s65, 0
	s_add_i32 s66, s67, s50
	global_load_lds_dwordx4 v[228:229], off
	v_lshl_add_u64 v[230:231], s[64:65], 0, v[172:173]
	s_mov_b32 m0, s66
	v_lshl_add_u64 v[232:233], s[64:65], 0, v[182:183]
	global_load_lds_dwordx4 v[230:231], off
	s_add_i32 m0, s66, 0x2000
	v_lshl_add_u64 v[234:235], s[4:5], 0, v[186:187]
	global_load_lds_dwordx4 v[232:233], off
	s_mov_b32 m0, s51
	v_lshl_add_u64 v[236:237], s[4:5], 0, v[184:185]
	global_load_lds_dwordx4 v[234:235], off
	s_mov_b32 m0, s52
	s_nop 0
	global_load_lds_dwordx4 v[236:237], off
	s_waitcnt vmcnt(8)
	s_waitcnt lgkmcnt(0)
	s_barrier
	s_waitcnt lgkmcnt(0)
	v_mfma_f32_16x16x32_bf16 v[60:63], v[120:123], v[160:163], v[60:63]
	v_mfma_f32_16x16x32_bf16 v[56:59], v[128:131], v[160:163], v[56:59]
	v_mfma_f32_16x16x32_bf16 v[48:51], v[120:123], v[168:171], v[48:51]
	v_mfma_f32_16x16x32_bf16 v[40:43], v[128:131], v[168:171], v[40:43]
	v_mfma_f32_16x16x32_bf16 v[32:35], v[120:123], v[196:199], v[32:35]
	v_mfma_f32_16x16x32_bf16 v[24:27], v[128:131], v[196:199], v[24:27]
	v_mfma_f32_16x16x32_bf16 v[16:19], v[120:123], v[218:221], v[16:19]
	v_mfma_f32_16x16x32_bf16 v[8:11], v[128:131], v[218:221], v[8:11]
	v_mfma_f32_16x16x32_bf16 v[60:63], v[124:127], v[164:167], v[60:63]
	v_mfma_f32_16x16x32_bf16 v[56:59], v[132:135], v[164:167], v[56:59]
	v_mfma_f32_16x16x32_bf16 v[48:51], v[124:127], v[192:195], v[48:51]
	v_mfma_f32_16x16x32_bf16 v[40:43], v[132:135], v[192:195], v[40:43]
	v_mfma_f32_16x16x32_bf16 v[32:35], v[124:127], v[200:203], v[32:35]
	v_mfma_f32_16x16x32_bf16 v[24:27], v[132:135], v[200:203], v[24:27]
	v_mfma_f32_16x16x32_bf16 v[16:19], v[124:127], v[222:225], v[16:19]
	v_mfma_f32_16x16x32_bf16 v[8:11], v[132:135], v[222:225], v[8:11]
	v_mfma_f32_16x16x32_bf16 v[52:55], v[144:147], v[160:163], v[52:55]
	v_mfma_f32_16x16x32_bf16 v[44:47], v[152:155], v[160:163], v[44:47]
	v_mfma_f32_16x16x32_bf16 v[36:39], v[144:147], v[168:171], v[36:39]
	v_mfma_f32_16x16x32_bf16 v[28:31], v[152:155], v[168:171], v[28:31]
	v_mfma_f32_16x16x32_bf16 v[20:23], v[144:147], v[196:199], v[20:23]
	v_mfma_f32_16x16x32_bf16 v[12:15], v[152:155], v[196:199], v[12:15]
	v_mfma_f32_16x16x32_bf16 v[4:7], v[144:147], v[218:221], v[4:7]
	v_mfma_f32_16x16x32_bf16 v[0:3], v[152:155], v[218:221], v[0:3]
	v_mfma_f32_16x16x32_bf16 v[52:55], v[148:151], v[164:167], v[52:55]
	v_mfma_f32_16x16x32_bf16 v[44:47], v[156:159], v[164:167], v[44:47]
	v_mfma_f32_16x16x32_bf16 v[36:39], v[148:151], v[192:195], v[36:39]
	v_mfma_f32_16x16x32_bf16 v[28:31], v[156:159], v[192:195], v[28:31]
	v_mfma_f32_16x16x32_bf16 v[20:23], v[148:151], v[200:203], v[20:23]
	v_mfma_f32_16x16x32_bf16 v[12:15], v[156:159], v[200:203], v[12:15]
	v_mfma_f32_16x16x32_bf16 v[4:7], v[148:151], v[222:225], v[4:7]
	v_mfma_f32_16x16x32_bf16 v[0:3], v[156:159], v[222:225], v[0:3]
	s_barrier
	s_add_i32 s64, 0, 0x18000
	s_add_i32 s65, 0, 0x1c000
	v_add_u32_e32 v132, s64, v215
	v_add_u32_e32 v156, s65, v215
	ds_read_b128 v[120:123], v132
	ds_read_b128 v[124:127], v132 offset:1024
	ds_read_b128 v[128:131], v132 offset:2048
	ds_read_b128 v[132:135], v132 offset:3072
	ds_read_b128 v[144:147], v156
	ds_read_b128 v[148:151], v156 offset:1024
	ds_read_b128 v[152:155], v156 offset:2048
	ds_read_b128 v[156:159], v156 offset:3072
	s_add_u32 s4, s4, s26
	s_addc_u32 s5, s5, 0
	s_mov_b32 m0, s53
	ds_read_b128 v[160:163], v217 offset:32768
	ds_read_b128 v[164:167], v217 offset:33792
	ds_read_b128 v[168:171], v217 offset:34816
	ds_read_b128 v[192:195], v217 offset:35840
	ds_read_b128 v[196:199], v217 offset:36864
	ds_read_b128 v[200:203], v217 offset:37888
	ds_read_b128 v[218:221], v217 offset:38912
	ds_read_b128 v[222:225], v217 offset:39936
	global_load_lds_dwordx4 v186, s[4:5]
	s_mov_b32 m0, s54
	s_nop 0
	global_load_lds_dwordx4 v184, s[4:5]
	s_waitcnt vmcnt(8)
	s_waitcnt lgkmcnt(0)
	s_barrier
	s_waitcnt lgkmcnt(0)
	v_mfma_f32_16x16x32_bf16 v[140:143], v[120:123], v[160:163], v[140:143]
	v_mfma_f32_16x16x32_bf16 v[136:139], v[128:131], v[160:163], v[136:139]
	v_mfma_f32_16x16x32_bf16 v[108:111], v[120:123], v[168:171], v[108:111]
	v_mfma_f32_16x16x32_bf16 v[104:107], v[128:131], v[168:171], v[104:107]
	v_mfma_f32_16x16x32_bf16 v[96:99], v[120:123], v[196:199], v[96:99]
	v_mfma_f32_16x16x32_bf16 v[88:91], v[128:131], v[196:199], v[88:91]
	v_mfma_f32_16x16x32_bf16 v[80:83], v[120:123], v[218:221], v[80:83]
	v_mfma_f32_16x16x32_bf16 v[72:75], v[128:131], v[218:221], v[72:75]
	v_mfma_f32_16x16x32_bf16 v[140:143], v[124:127], v[164:167], v[140:143]
	v_mfma_f32_16x16x32_bf16 v[136:139], v[132:135], v[164:167], v[136:139]
	v_mfma_f32_16x16x32_bf16 v[108:111], v[124:127], v[192:195], v[108:111]
	v_mfma_f32_16x16x32_bf16 v[104:107], v[132:135], v[192:195], v[104:107]
	v_mfma_f32_16x16x32_bf16 v[96:99], v[124:127], v[200:203], v[96:99]
	v_mfma_f32_16x16x32_bf16 v[88:91], v[132:135], v[200:203], v[88:91]
	v_mfma_f32_16x16x32_bf16 v[80:83], v[124:127], v[222:225], v[80:83]
	v_mfma_f32_16x16x32_bf16 v[72:75], v[132:135], v[222:225], v[72:75]
	v_mfma_f32_16x16x32_bf16 v[116:119], v[144:147], v[160:163], v[116:119]
	v_mfma_f32_16x16x32_bf16 v[112:115], v[152:155], v[160:163], v[112:115]
	v_mfma_f32_16x16x32_bf16 v[100:103], v[144:147], v[168:171], v[100:103]
	v_mfma_f32_16x16x32_bf16 v[92:95], v[152:155], v[168:171], v[92:95]
	v_mfma_f32_16x16x32_bf16 v[84:87], v[144:147], v[196:199], v[84:87]
	v_mfma_f32_16x16x32_bf16 v[76:79], v[152:155], v[196:199], v[76:79]
	v_mfma_f32_16x16x32_bf16 v[68:71], v[144:147], v[218:221], v[68:71]
	v_mfma_f32_16x16x32_bf16 v[64:67], v[152:155], v[218:221], v[64:67]
	v_mfma_f32_16x16x32_bf16 v[116:119], v[148:151], v[164:167], v[116:119]
	v_mfma_f32_16x16x32_bf16 v[112:115], v[156:159], v[164:167], v[112:115]
	v_mfma_f32_16x16x32_bf16 v[100:103], v[148:151], v[192:195], v[100:103]
	v_mfma_f32_16x16x32_bf16 v[92:95], v[156:159], v[192:195], v[92:95]
	v_mfma_f32_16x16x32_bf16 v[84:87], v[148:151], v[200:203], v[84:87]
	v_mfma_f32_16x16x32_bf16 v[76:79], v[156:159], v[200:203], v[76:79]
	v_mfma_f32_16x16x32_bf16 v[68:71], v[148:151], v[222:225], v[68:71]
	v_mfma_f32_16x16x32_bf16 v[64:67], v[156:159], v[222:225], v[64:67]
	s_barrier
	s_add_i32 s4, s64, s50
	v_lshl_add_u64 v[226:227], v[226:227], 0, s[36:37]
	s_mov_b32 m0, s4
	ds_read_b128 v[160:163], v217 offset:49152
	ds_read_b128 v[164:167], v217 offset:50176
	ds_read_b128 v[168:171], v217 offset:51200
	ds_read_b128 v[192:195], v217 offset:52224
	ds_read_b128 v[196:199], v217 offset:53248
	ds_read_b128 v[200:203], v217 offset:54272
	ds_read_b128 v[218:221], v217 offset:55296
	ds_read_b128 v[222:225], v217 offset:56320
	global_load_lds_dwordx4 v[226:227], off
	v_lshl_add_u64 v[226:227], v[228:229], 0, s[36:37]
	s_add_i32 m0, s4, 0x2000
	s_add_i32 s4, s65, s50
	global_load_lds_dwordx4 v[226:227], off
	v_lshl_add_u64 v[226:227], v[230:231], 0, s[36:37]
	s_mov_b32 m0, s4
	s_nop 0
	global_load_lds_dwordx4 v[226:227], off
	v_lshl_add_u64 v[226:227], v[232:233], 0, s[36:37]
	s_add_i32 m0, s4, 0x2000
	s_nop 0
	global_load_lds_dwordx4 v[226:227], off
	v_lshl_add_u64 v[226:227], v[234:235], 0, s[36:37]
	s_mov_b32 m0, s56
	s_nop 0
	global_load_lds_dwordx4 v[226:227], off
	v_lshl_add_u64 v[226:227], v[236:237], 0, s[36:37]
	s_mov_b32 m0, s57
	s_nop 0
	global_load_lds_dwordx4 v[226:227], off
	s_waitcnt vmcnt(8)
	s_waitcnt lgkmcnt(0)
	s_barrier
	s_waitcnt lgkmcnt(0)
	v_mfma_f32_16x16x32_bf16 v[60:63], v[120:123], v[160:163], v[60:63]
	v_mfma_f32_16x16x32_bf16 v[56:59], v[128:131], v[160:163], v[56:59]
	v_mfma_f32_16x16x32_bf16 v[48:51], v[120:123], v[168:171], v[48:51]
	v_mfma_f32_16x16x32_bf16 v[40:43], v[128:131], v[168:171], v[40:43]
	v_mfma_f32_16x16x32_bf16 v[32:35], v[120:123], v[196:199], v[32:35]
	v_mfma_f32_16x16x32_bf16 v[24:27], v[128:131], v[196:199], v[24:27]
	v_mfma_f32_16x16x32_bf16 v[16:19], v[120:123], v[218:221], v[16:19]
	v_mfma_f32_16x16x32_bf16 v[8:11], v[128:131], v[218:221], v[8:11]
	v_mfma_f32_16x16x32_bf16 v[60:63], v[124:127], v[164:167], v[60:63]
	v_mfma_f32_16x16x32_bf16 v[56:59], v[132:135], v[164:167], v[56:59]
	v_mfma_f32_16x16x32_bf16 v[48:51], v[124:127], v[192:195], v[48:51]
	v_mfma_f32_16x16x32_bf16 v[40:43], v[132:135], v[192:195], v[40:43]
	v_mfma_f32_16x16x32_bf16 v[32:35], v[124:127], v[200:203], v[32:35]
	v_mfma_f32_16x16x32_bf16 v[24:27], v[132:135], v[200:203], v[24:27]
	v_mfma_f32_16x16x32_bf16 v[16:19], v[124:127], v[222:225], v[16:19]
	v_mfma_f32_16x16x32_bf16 v[8:11], v[132:135], v[222:225], v[8:11]
	v_mfma_f32_16x16x32_bf16 v[52:55], v[144:147], v[160:163], v[52:55]
	v_mfma_f32_16x16x32_bf16 v[44:47], v[152:155], v[160:163], v[44:47]
	v_mfma_f32_16x16x32_bf16 v[36:39], v[144:147], v[168:171], v[36:39]
	v_mfma_f32_16x16x32_bf16 v[28:31], v[152:155], v[168:171], v[28:31]
	v_mfma_f32_16x16x32_bf16 v[20:23], v[144:147], v[196:199], v[20:23]
	v_mfma_f32_16x16x32_bf16 v[12:15], v[152:155], v[196:199], v[12:15]
	v_mfma_f32_16x16x32_bf16 v[4:7], v[144:147], v[218:221], v[4:7]
	v_mfma_f32_16x16x32_bf16 v[0:3], v[152:155], v[218:221], v[0:3]
	v_mfma_f32_16x16x32_bf16 v[52:55], v[148:151], v[164:167], v[52:55]
	v_mfma_f32_16x16x32_bf16 v[44:47], v[156:159], v[164:167], v[44:47]
	v_mfma_f32_16x16x32_bf16 v[36:39], v[148:151], v[192:195], v[36:39]
	v_mfma_f32_16x16x32_bf16 v[28:31], v[156:159], v[192:195], v[28:31]
	v_mfma_f32_16x16x32_bf16 v[20:23], v[148:151], v[200:203], v[20:23]
	v_mfma_f32_16x16x32_bf16 v[12:15], v[156:159], v[200:203], v[12:15]
	v_mfma_f32_16x16x32_bf16 v[4:7], v[148:151], v[222:225], v[4:7]
	v_mfma_f32_16x16x32_bf16 v[0:3], v[156:159], v[222:225], v[0:3]
	s_barrier
	s_add_u32 s46, s46, 0x100
	s_addc_u32 s47, s47, 0
	s_add_u32 s48, s48, 0x100
	s_addc_u32 s49, s49, 0
	s_cmp_ge_u32 s63, s35
	s_mov_b32 s4, s63
	s_cbranch_scc0 .LBB0_1412
	s_and_b64 vcc, exec, s[38:39]
	s_cbranch_vccz .LBB0_1415
	s_barrier
